# split grid barrier after the fix-up phase too: wait + acquire only before the merge GEMM's first load of the attention output
# speedup vs baseline: 1.0130x; 1.0039x over previous
;     __device__ bool next(int i, Unit& u) const {
;         const long L = (long)i * G + c; if (L >= nwg) return false;
;         int wgid = (int)L; { const int q = nwg / NXCD, r = nwg % NXCD, xcd = wgid % NXCD, off = wgid / NXCD; wgid = (xcd < r ? xcd * (q + 1) : r * (q + 1) + (xcd - r) * q) + off; }
;         const int nig = WGM * nN, gid = wgid / nig, fm = gid * WGM, gsz = (nM - fm) < WGM ? (nM - fm) : WGM;
;         u.pm = fm + ((wgid % nig) % gsz); u.pn = (wgid % nig) / gsz; return true;
;     }
; __global__ void __launch_bounds__(512, 2) mega_fwd(Params p) {
;     ...
;     if (IN(7)) {
;         bf16_t* MG = (bf16_t*)(ws + WS_R1 + R1_MG);
;         pg8::Gemm g0{HM, (const bf16_t*)(ws + WS_WPM), T_TOK, 1024, 1024}; pg8::Gemm g1{ATT, (const bf16_t*)(ws + WS_WPA), T_TOK, 1024, 512};
;         pg8::StaticOrder S; S.init(T_TOK, 1024, G, bid);
;         EpiRatio E0{R2}; EpiMerge2 E1{R2, MG};
;         pg8::gemm_phase2<EpiRatio, EpiMerge2>(lds, g0, g1, S, E0, E1);
.LBB0_703:
	s_mov_b32 s101, 0
	s_mov_b32 s98, 0
	s_cmp_gt_i32 s91, 7
	s_cselect_b64 s[0:1], -1, 0
	s_and_b64 s[2:3], s[8:9], s[0:1]
	s_andn2_b64 vcc, exec, s[2:3]
	s_cbranch_vccnz .LBB0_753
	s_cmp_eq_u32 s82, 0x100
	s_cselect_b32 s98, 1, 0
	s_cmp_eq_u32 s99, 1
	s_cselect_b32 s98, s98, 0
	s_cmp_eq_u32 s99, 1
	s_cbranch_scc0 .Lp7e_skip
	s_cmpk_gt_i32 s84, 0xff
	s_cbranch_scc1 .Lp7e_skip
	s_mov_b32 s101, 1
	v_readfirstlane_b32 s30, v212
	s_ashr_i32 s31, s84, 31
	s_lshr_b32 s2, s31, 29
	s_add_i32 s5, s84, s2
	s_and_b32 s2, s5, -8
	s_sub_i32 s8, s84, s2
	s_cmp_gt_i32 s8, -1
	s_cbranch_scc0 .Lp7e_757
	s_lshl_b32 s4, s8, 5
	s_cbranch_execz .Lp7e_758
	s_branch .Lp7e_759

; __device__ __forceinline__ unsigned xb_ld(unsigned* p)              { return __hip_atomic_load(p, __ATOMIC_RELAXED, __HIP_MEMORY_SCOPE_AGENT); }
; __device__ __forceinline__ unsigned xb_add(unsigned* p, unsigned v) { return __hip_atomic_fetch_add(p, v, __ATOMIC_RELAXED, __HIP_MEMORY_SCOPE_AGENT); }
; #define XB_SPIN(cond, bar) do { unsigned _sp = 0; while (cond) { __builtin_amdgcn_s_sleep(1); \
;     if ((++_sp & 255u) == 0u) { if (xb_ld(&(bar)[XB_TMO])) break; if (_sp > XB_SPIN_CAP) { atomicAdd(&(bar)[XB_TMO], 1u); break; } } } } while (0)
; __device__ __forceinline__ void xcd_barrier(const XcdBarrier& b) {
;     ...
;         const unsigned old = xb_add(&bar[XB_XSUB(b.x)], 1u);
;         const unsigned gen = old / nloc;
;         if (old + 1u == (gen + 1u) * nloc) {
;             __builtin_amdgcn_fence(__ATOMIC_RELEASE, "agent");
;             asm volatile("s_waitcnt vmcnt(0)" ::: "memory");
;             const unsigned og = xb_add(&bar[XB_TOP], 1u);
;             const unsigned tg = og / nx;
;             if (og + 1u == (tg + 1u) * nx) xb_add(&bar[XB_TOPGEN], 1u);
;             else XB_SPIN(xb_ld(&bar[XB_TOPGEN]) == tg, bar);
;             __builtin_amdgcn_fence(__ATOMIC_ACQUIRE, "agent");
;             xb_add(&bar[XB_XGEN(b.x)], 1u);
;             asm volatile("s_waitcnt vmcnt(0)" ::: "memory");
;         } else {
;             XB_SPIN(xb_ld(&bar[XB_XGEN(b.x)]) == gen, bar);
.LBB0_720:
	v_readlane_b32 s4, v254, 3
	s_lshl_b32 s4, s4, 8
	s_add_u32 s4, s92, s4
	s_addc_u32 s5, s93, 0
	v_mov_b32_e32 v1, 0x1000
	v_mov_b32_e32 v3, 1
	global_atomic_add v3, v1, v3, s[4:5] offset:1024 sc0
	v_cvt_f32_u32_e32 v1, v2
	v_sub_u32_e32 v4, 0, v2
	v_rcp_iflag_f32_e32 v1, v1
	s_nop 0
	v_mul_f32_e32 v1, 0x4f7ffffe, v1
	v_cvt_u32_f32_e32 v1, v1
	v_mul_lo_u32 v4, v4, v1
	v_mul_hi_u32 v4, v1, v4
	v_add_u32_e32 v1, v1, v4
	s_waitcnt vmcnt(0)
	v_mul_hi_u32 v1, v3, v1
	v_mul_lo_u32 v4, v1, v2
	v_sub_u32_e32 v4, v3, v4
	v_add_u32_e32 v5, 1, v1
	v_cmp_ge_u32_e32 vcc, v4, v2
	v_add_u32_e32 v3, 1, v3
	s_nop 0
	v_cndmask_b32_e32 v1, v1, v5, vcc
	v_sub_u32_e32 v5, v4, v2
	v_cndmask_b32_e32 v4, v4, v5, vcc
	v_add_u32_e32 v5, 1, v1
	v_cmp_ge_u32_e32 vcc, v4, v2
	s_nop 1
	v_cndmask_b32_e32 v1, v1, v5, vcc
	v_mul_lo_u32 v4, v2, v1
	v_add_u32_e32 v2, v4, v2
	v_cmp_ne_u32_e32 vcc, v3, v2
	s_and_saveexec_b64 s[8:9], vcc
	s_xor_b64 s[8:9], exec, s[8:9]
	s_cbranch_execz .LBB0_734
	s_cmp_eq_u32 s98, 1
	s_cbranch_scc1 .Lsk6_nl
	s_waitcnt lgkmcnt(0)
	v_mov_b32_e32 v0, 0x2000
	global_load_dword v0, v0, s[4:5] offset:1024 sc1
	s_add_u32 s14, s4, 0x2400
	s_addc_u32 s15, s5, 0
	s_waitcnt vmcnt(0)
	v_cmp_eq_u32_e32 vcc, v0, v1
	s_and_saveexec_b64 s[10:11], vcc
	s_cbranch_execz .LBB0_733
	s_add_u32 s12, s88, 0xffc0200
	s_addc_u32 s13, s89, 0
	s_mov_b32 s26, 1
	s_mov_b64 s[16:17], 0
	v_mov_b32_e32 v0, 0
	s_branch .LBB0_724

; __device__ __forceinline__ unsigned xb_ld(unsigned* p)              { return __hip_atomic_load(p, __ATOMIC_RELAXED, __HIP_MEMORY_SCOPE_AGENT); }
; __device__ __forceinline__ unsigned xb_add(unsigned* p, unsigned v) { return __hip_atomic_fetch_add(p, v, __ATOMIC_RELAXED, __HIP_MEMORY_SCOPE_AGENT); }
; #define XB_SPIN(cond, bar) do { unsigned _sp = 0; while (cond) { __builtin_amdgcn_s_sleep(1); \
;     if ((++_sp & 255u) == 0u) { if (xb_ld(&(bar)[XB_TMO])) break; if (_sp > XB_SPIN_CAP) { atomicAdd(&(bar)[XB_TMO], 1u); break; } } } } while (0)
; __device__ __forceinline__ void xcd_barrier(const XcdBarrier& b) {
;     ...
;         const unsigned old = xb_add(&bar[XB_XSUB(b.x)], 1u);
;         const unsigned gen = old / nloc;
;         if (old + 1u == (gen + 1u) * nloc) {
;             __builtin_amdgcn_fence(__ATOMIC_RELEASE, "agent");
;             asm volatile("s_waitcnt vmcnt(0)" ::: "memory");
;             const unsigned og = xb_add(&bar[XB_TOP], 1u);
;             const unsigned tg = og / nx;
;             if (og + 1u == (tg + 1u) * nx) xb_add(&bar[XB_TOPGEN], 1u);
;             else XB_SPIN(xb_ld(&bar[XB_TOPGEN]) == tg, bar);
;             __builtin_amdgcn_fence(__ATOMIC_ACQUIRE, "agent");
;             xb_add(&bar[XB_XGEN(b.x)], 1u);
;             asm volatile("s_waitcnt vmcnt(0)" ::: "memory");
;         } else {
;             XB_SPIN(xb_ld(&bar[XB_XGEN(b.x)]) == gen, bar);
;             __builtin_amdgcn_fence(__ATOMIC_ACQUIRE, "agent");
;             asm volatile("s_waitcnt vmcnt(0)" ::: "memory");
.LBB0_733:
	s_or_b64 exec, exec, s[10:11]
.Lsk6_nl:
	s_waitcnt vmcnt(0)
	buffer_inv sc1
	s_waitcnt vmcnt(0)
.LBB0_734:
	s_andn2_saveexec_b64 s[8:9], s[8:9]
	s_cbranch_execz .LBB0_752
	s_mov_b64 s[8:9], exec
	buffer_wbl2 sc1
	s_waitcnt lgkmcnt(0)
	s_waitcnt vmcnt(0)
	v_mbcnt_lo_u32_b32 v1, s8, 0
	v_mbcnt_hi_u32_b32 v1, s9, v1
	v_cmp_eq_u32_e32 vcc, 0, v1
	s_and_saveexec_b64 s[10:11], vcc
	s_cbranch_execz .LBB0_737
	s_bcnt1_i32_b64 s8, s[8:9]
	v_mov_b32_e32 v2, 0xffc3000
	v_mov_b32_e32 v3, s8
	global_atomic_add v2, v2, v3, s[88:89] offset:1024 sc0
.LBB0_737:
	s_or_b64 exec, exec, s[10:11]
	v_cvt_f32_u32_e32 v3, v0
	s_waitcnt vmcnt(0)
	v_readfirstlane_b32 s8, v2
	s_add_u32 s10, s88, 0xffc3500
	s_addc_u32 s11, s89, 0
	v_rcp_iflag_f32_e32 v3, v3
	v_add_u32_e32 v1, s8, v1
	v_add_u32_e32 v4, 1, v1
	s_mov_b64 s[12:13], -1
	v_mul_f32_e32 v2, 0x4f7ffffe, v3
	v_cvt_u32_f32_e32 v2, v2
	v_sub_u32_e32 v3, 0, v0
	v_mul_lo_u32 v3, v3, v2
	v_mul_hi_u32 v3, v2, v3
	v_add_u32_e32 v2, v2, v3
	v_mul_hi_u32 v2, v1, v2
	v_mul_lo_u32 v3, v2, v0
	v_sub_u32_e32 v1, v1, v3
	v_add_u32_e32 v5, 1, v2
	v_cmp_ge_u32_e32 vcc, v1, v0
	v_sub_u32_e32 v3, v1, v0
	s_nop 0
	v_cndmask_b32_e32 v2, v2, v5, vcc
	v_cndmask_b32_e32 v1, v1, v3, vcc
	v_add_u32_e32 v3, 1, v2
	v_cmp_ge_u32_e32 vcc, v1, v0
	s_nop 1
	v_cndmask_b32_e32 v2, v2, v3, vcc
	v_mul_lo_u32 v1, v0, v2
	v_add_u32_e32 v0, v1, v0
	v_cmp_ne_u32_e32 vcc, v4, v0
	v_mov_b64_e32 v[0:1], s[10:11]
	s_and_saveexec_b64 s[8:9], vcc
	s_cbranch_execz .LBB0_749
	s_cmp_eq_u32 s98, 1
	s_cbranch_scc0 .Lsk6_ld_no
	s_mov_b64 s[16:17], 0
	s_branch .Lsk6_ld
.Lsk6_ld_no:
	v_mov_b32_e32 v0, 0
	global_load_dword v1, v0, s[10:11] sc1
	s_mov_b64 s[16:17], 0
	s_waitcnt vmcnt(0)
	v_cmp_eq_u32_e32 vcc, v1, v2
	s_and_saveexec_b64 s[14:15], vcc
	s_cbranch_execz .LBB0_748
	s_add_u32 s12, s88, 0xffc0200
	s_addc_u32 s13, s89, 0
	s_mov_b32 s26, 1
	s_branch .LBB0_741

; __device__ __forceinline__ unsigned xb_ld(unsigned* p)              { return __hip_atomic_load(p, __ATOMIC_RELAXED, __HIP_MEMORY_SCOPE_AGENT); }
; __device__ __forceinline__ unsigned xb_add(unsigned* p, unsigned v) { return __hip_atomic_fetch_add(p, v, __ATOMIC_RELAXED, __HIP_MEMORY_SCOPE_AGENT); }
; #define XB_SPIN(cond, bar) do { unsigned _sp = 0; while (cond) { __builtin_amdgcn_s_sleep(1); \
;     if ((++_sp & 255u) == 0u) { if (xb_ld(&(bar)[XB_TMO])) break; if (_sp > XB_SPIN_CAP) { atomicAdd(&(bar)[XB_TMO], 1u); break; } } } } while (0)
; __device__ __forceinline__ void xcd_barrier(const XcdBarrier& b) {
;     ...
;             else XB_SPIN(xb_ld(&bar[XB_TOPGEN]) == tg, bar);
;             __builtin_amdgcn_fence(__ATOMIC_ACQUIRE, "agent");
;             xb_add(&bar[XB_XGEN(b.x)], 1u);
.Lsk6_ld:
	v_mov_b64_e32 v[0:1], s[12:13]
	s_orn2_b64 s[12:13], s[16:17], exec

; #define PG8_LDA(dst, b, h) do { _Pragma("unroll") for (int m = 0; m < 4; ++m) _Pragma("unroll") for (int k = 0; k < 2; ++k) dst[m][k] = *(const LAS bf16x8*)(lds + PG8_SA(b, h) + aoff + m * 2048 + k * 1024); } while (0)
; #define PG8_LDB(dst, b, h) do { _Pragma("unroll") for (int n = 0; n < 2; ++n) _Pragma("unroll") for (int k = 0; k < 2; ++k) dst[n][k] = *(const LAS bf16x8*)(lds + PG8_SB(b, h) + boff + n * 2048 + k * 1024); } while (0)
; #define PG8_MMA(ai, bj, At, Bt) do { __builtin_amdgcn_s_setprio(1); _Pragma("unroll") for (int m = 0; m < 4; ++m) _Pragma("unroll") for (int n = 0; n < 2; ++n) _Pragma("unroll") for (int k = 0; k < 2; ++k) \
;         acc[ai][bj][m][n] = __builtin_amdgcn_mfma_f32_16x16x32_bf16(Bt[n][k], At[m][k], acc[ai][bj][m][n], 0, 0, 0); __builtin_amdgcn_s_setprio(0); } while (0)
; #define PG8_WAIT_V(n) asm volatile("s_waitcnt vmcnt(" #n ")" ::: "memory")
; #define PG8_WAIT_L(n) asm volatile("s_waitcnt lgkmcnt(" #n ")" ::: "memory")
; #define PG8_BAR __builtin_amdgcn_s_barrier()
; template <class EpiMid, class EpiEnd>
; __device__ __forceinline__ void gemm_phase2(LAS unsigned char* lds, const Gemm g0, const Gemm g1, const StaticOrder& S, const EpiMid& Emid, const EpiEnd& Eend) {
;     ...
;             for (int t = 0; t < nt; t += 2) {
;                 const bool last = (t == nt - 2);
;                 const char* a1 = cA + (size_t)(t + 1) * kstep;
;                 const char* a2 = last ? nA : cA + (size_t)(t + 2) * kstep; const char* b2 = last ? nB : cB + (size_t)(t + 2) * kstep;
;                 const char* a3 = a2 + kstep; const char* b3 = b2 + kstep;
;                 const size_t h2 = last ? hsn : hs;
;                 const unsigned K2 = last ? Kn : Kc;
;                 PG8_LDB(B0, 0, 0); PG8_SCHED; PG8_LDA(At, 0, 0); PG8_STAGE2(PG8_SA(1, 1), a1 + hs, rA2, Kc);
;                 PG8_WAIT_L(8); PG8_BAR; PG8_WAIT_L(0); PG8_MMA(0, 0, At, B0); PG8_BAR; PG8_SCHED;
;                 PG8_LDB(B1, 0, 1); PG8_STAGE2(PG8_SB(0, 0), b2, rB2, K2);
;                 PG8_BAR; PG8_WAIT_L(0); PG8_MMA(0, 1, At, B1); PG8_BAR;
;                 PG8_LDA(At, 0, 1); PG8_STAGE2(PG8_SA(0, 0), a2, rA2, K2);
;                 PG8_BAR; PG8_WAIT_L(0); PG8_MMA(1, 0, At, B0); PG8_BAR; PG8_SCHED;
;                 PG8_STAGE2(PG8_SB(0, 1), b2 + h2, rB2, K2);
;                 PG8_WAIT_V(6); PG8_BAR; PG8_MMA(1, 1, At, B1); PG8_BAR;
.LBB0_772:
	s_cmp_eq_u32 s62, s24
	s_cselect_b64 s[64:65], -1, 0
	s_cmp_eq_u32 s98, 1
	s_cbranch_scc0 .Lw6_skip
	s_and_b64 s[96:97], s[64:65], s[22:23]
	s_cbranch_scc0 .Lw6_skip
	s_mov_b32 s98, 0
	v_readfirstlane_b32 s96, v212
	s_nop 3
	s_cmp_lg_u32 s96, 0
	s_cbranch_scc1 .Lw6_bar
	v_readlane_b32 s96, v254, 3
	s_nop 3
	s_lshl_b32 s96, s96, 8
	v_mov_b32_e32 v250, 0xffc3500
	v_mov_b32_e32 v251, 0xffc2400
	v_add_u32_e32 v251, s96, v251
	s_mov_b32 s96, 0
.Lw6_spin:
	global_load_dword v252, v250, s[88:89] sc1
	global_load_dword v253, v251, s[88:89] sc1
	s_waitcnt vmcnt(0)
	v_min_u32_e32 v252, v252, v253
	s_nop 1
	v_readfirstlane_b32 s97, v252
	s_nop 3
	s_cmp_ge_u32 s97, 7
	s_cbranch_scc1 .Lw6_acq
	s_sleep 1
	s_add_i32 s96, s96, 1
	s_cmp_lt_u32 s96, 0x40000
	s_cbranch_scc1 .Lw6_spin
.Lw6_acq:
	buffer_inv sc1
	s_waitcnt vmcnt(0)
.Lw6_bar:
	s_barrier
.Lw6_skip:
	s_add_i32 s54, s54, 2
	s_add_u32 s26, s20, s24
	v_add_u32_e32 v0, s48, v159
	s_addc_u32 s27, s21, s25
	ds_read_b128 v[134:137], v0
	ds_read_b128 v[138:141], v0 offset:1024
	ds_read_b128 v[142:145], v0 offset:2048
	ds_read_b128 v[146:149], v0 offset:3072
	s_add_u32 s28, s26, 0x100
	s_addc_u32 s29, s27, 0
	s_and_b64 s[26:27], s[64:65], exec
	s_cselect_b32 s27, s56, s29
	s_cselect_b32 s26, s57, s28
	s_cselect_b32 s63, 0, 0
	s_cselect_b32 s66, s55, s53
	s_add_u32 s67, s60, s24
	s_addc_u32 s68, s61, s25
	s_and_b64 s[28:29], s[64:65], exec
	s_cselect_b32 s29, s58, s68
	s_cselect_b32 s28, s59, s67
	v_lshl_add_u64 v[150:151], v[2:3], 0, s[24:25]
	s_add_i32 m0, s36, 0xc000
	ds_read_b128 v[170:173], v165
	ds_read_b128 v[174:177], v165 offset:1024
	ds_read_b128 v[178:181], v165 offset:2048
	ds_read_b128 v[182:185], v165 offset:3072
	ds_read_b128 v[186:189], v165 offset:4096
	ds_read_b128 v[190:193], v165 offset:5120
	ds_read_b128 v[194:197], v165 offset:6144
	ds_read_b128 v[198:201], v165 offset:7168
	global_load_lds_dwordx4 v[150:151], off
	v_lshl_add_u64 v[150:151], v[132:133], 0, s[24:25]
	s_add_i32 m0, s36, 0xe000
	s_nop 0
	global_load_lds_dwordx4 v[150:151], off
	s_waitcnt lgkmcnt(8)
	s_barrier
	s_waitcnt lgkmcnt(0)
	s_setprio 1
	s_waitcnt lgkmcnt(0)
	v_mfma_f32_16x16x32_bf16 v[128:131], v[134:137], v[170:173], v[128:131]
	v_mfma_f32_16x16x32_bf16 v[124:127], v[142:145], v[170:173], v[124:127]
	v_mfma_f32_16x16x32_bf16 v[120:123], v[134:137], v[178:181], v[120:123]
	v_mfma_f32_16x16x32_bf16 v[116:119], v[142:145], v[178:181], v[116:119]
	v_mfma_f32_16x16x32_bf16 v[112:115], v[134:137], v[186:189], v[112:115]
	v_mfma_f32_16x16x32_bf16 v[108:111], v[142:145], v[186:189], v[108:111]
	v_mfma_f32_16x16x32_bf16 v[104:107], v[134:137], v[194:197], v[104:107]
	v_mfma_f32_16x16x32_bf16 v[100:103], v[142:145], v[194:197], v[100:103]
	v_mfma_f32_16x16x32_bf16 v[128:131], v[138:141], v[174:177], v[128:131]
	v_mfma_f32_16x16x32_bf16 v[124:127], v[146:149], v[174:177], v[124:127]
	v_mfma_f32_16x16x32_bf16 v[120:123], v[138:141], v[182:185], v[120:123]
	v_mfma_f32_16x16x32_bf16 v[116:119], v[146:149], v[182:185], v[116:119]
	v_mfma_f32_16x16x32_bf16 v[112:115], v[138:141], v[190:193], v[112:115]
	v_mfma_f32_16x16x32_bf16 v[108:111], v[146:149], v[190:193], v[108:111]
	v_mfma_f32_16x16x32_bf16 v[104:107], v[138:141], v[198:201], v[104:107]
	v_mfma_f32_16x16x32_bf16 v[100:103], v[146:149], v[198:201], v[100:103]
	s_setprio 0
	s_barrier
	s_xor_b64 s[64:65], s[22:23], s[64:65]
	s_and_b64 s[64:65], s[64:65], exec
	v_add_u32_e32 v0, s49, v159
	s_cselect_b32 s64, 10, 9
	s_add_i32 s65, s48, s33
	ds_read_b128 v[202:205], v0
	ds_read_b128 v[206:209], v0 offset:1024
	ds_read_b128 v[214:217], v0 offset:2048
	ds_read_b128 v[218:221], v0 offset:3072
	v_lshl_or_b32 v0, v156, s64, v154
	s_mov_b32 m0, s65
	v_lshl_or_b32 v150, v158, s64, v154
	global_load_lds_dwordx4 v0, s[28:29]
	s_add_i32 m0, s65, 0x2000
	v_mov_b32_e32 v151, v1
	global_load_lds_dwordx4 v150, s[28:29]
	s_barrier
	s_waitcnt lgkmcnt(0)
	v_lshl_add_u64 v[210:211], s[28:29], 0, v[0:1]
	v_lshl_add_u64 v[222:223], s[28:29], 0, v[150:151]
	s_setprio 1
	s_waitcnt lgkmcnt(0)
	v_mfma_f32_16x16x32_bf16 v[96:99], v[202:205], v[170:173], v[96:99]
	v_mfma_f32_16x16x32_bf16 v[92:95], v[214:217], v[170:173], v[92:95]
	v_mfma_f32_16x16x32_bf16 v[88:91], v[202:205], v[178:181], v[88:91]
	v_mfma_f32_16x16x32_bf16 v[84:87], v[214:217], v[178:181], v[84:87]
	v_mfma_f32_16x16x32_bf16 v[80:83], v[202:205], v[186:189], v[80:83]
	v_mfma_f32_16x16x32_bf16 v[76:79], v[214:217], v[186:189], v[76:79]
	v_mfma_f32_16x16x32_bf16 v[72:75], v[202:205], v[194:197], v[72:75]
	v_mfma_f32_16x16x32_bf16 v[68:71], v[214:217], v[194:197], v[68:71]
	v_mfma_f32_16x16x32_bf16 v[96:99], v[206:209], v[174:177], v[96:99]
	v_mfma_f32_16x16x32_bf16 v[92:95], v[218:221], v[174:177], v[92:95]
	v_mfma_f32_16x16x32_bf16 v[88:91], v[206:209], v[182:185], v[88:91]
	v_mfma_f32_16x16x32_bf16 v[84:87], v[218:221], v[182:185], v[84:87]
	v_mfma_f32_16x16x32_bf16 v[80:83], v[206:209], v[190:193], v[80:83]
	v_mfma_f32_16x16x32_bf16 v[76:79], v[218:221], v[190:193], v[76:79]
	v_mfma_f32_16x16x32_bf16 v[72:75], v[206:209], v[198:201], v[72:75]
	v_mfma_f32_16x16x32_bf16 v[68:71], v[218:221], v[198:201], v[68:71]
	s_setprio 0
	s_mov_b32 m0, s36
	v_lshl_or_b32 v224, v155, s64, v154
	s_barrier
	ds_read_b128 v[170:173], v165 offset:16384
	ds_read_b128 v[174:177], v165 offset:17408
	ds_read_b128 v[178:181], v165 offset:18432
	ds_read_b128 v[182:185], v165 offset:19456
	ds_read_b128 v[186:189], v165 offset:20480
	ds_read_b128 v[190:193], v165 offset:21504
	ds_read_b128 v[194:197], v165 offset:22528
	ds_read_b128 v[198:201], v165 offset:23552
	global_load_lds_dwordx4 v224, s[26:27]
	v_lshl_or_b32 v226, v157, s64, v154
	s_mov_b32 m0, s37
	v_mov_b32_e32 v225, v1
	global_load_lds_dwordx4 v226, s[26:27]
	s_barrier
; #define PG8_LDA(dst, b, h) do { _Pragma("unroll") for (int m = 0; m < 4; ++m) _Pragma("unroll") for (int k = 0; k < 2; ++k) dst[m][k] = *(const LAS bf16x8*)(lds + PG8_SA(b, h) + aoff + m * 2048 + k * 1024); } while (0)
; #define PG8_LDB(dst, b, h) do { _Pragma("unroll") for (int n = 0; n < 2; ++n) _Pragma("unroll") for (int k = 0; k < 2; ++k) dst[n][k] = *(const LAS bf16x8*)(lds + PG8_SB(b, h) + boff + n * 2048 + k * 1024); } while (0)
; #define PG8_MMA(ai, bj, At, Bt) do { __builtin_amdgcn_s_setprio(1); _Pragma("unroll") for (int m = 0; m < 4; ++m) _Pragma("unroll") for (int n = 0; n < 2; ++n) _Pragma("unroll") for (int k = 0; k < 2; ++k) \
;         acc[ai][bj][m][n] = __builtin_amdgcn_mfma_f32_16x16x32_bf16(Bt[n][k], At[m][k], acc[ai][bj][m][n], 0, 0, 0); __builtin_amdgcn_s_setprio(0); } while (0)
; #define PG8_WAIT_L(n) asm volatile("s_waitcnt lgkmcnt(" #n ")" ::: "memory")
; #define PG8_BAR __builtin_amdgcn_s_barrier()
; #define PG8_SCHED __builtin_amdgcn_sched_barrier(0)
; #define PG8_STAGE2(bufoff, gbase, r2, Ksel) do { \
;         __builtin_amdgcn_global_load_lds((const unsigned*)((const char*)(gbase) + ((r2)[0] * (Ksel) + cb2[0])), (LAS unsigned*)(lds + (bufoff) + ldsw), 16, 0, 0); \
;         __builtin_amdgcn_global_load_lds((const unsigned*)((const char*)(gbase) + ((r2)[1] * (Ksel) + cb2[1])), (LAS unsigned*)(lds + (bufoff) + ldsw + 8192), 16, 0, 0); } while (0)
; #define PG8_LDA(dst, b, h) do { _Pragma("unroll") for (int m = 0; m < 4; ++m) _Pragma("unroll") for (int k = 0; k < 2; ++k) dst[m][k] = *(const LAS bf16x8*)(lds + PG8_SA(b, h) + aoff + m * 2048 + k * 1024); } while (0)
; #define PG8_BAR __builtin_amdgcn_s_barrier()
; template <class EpiMid, class EpiEnd>
; __device__ __forceinline__ void gemm_phase2(LAS unsigned char* lds, const Gemm g0, const Gemm g1, const StaticOrder& S, const EpiMid& Emid, const EpiEnd& Eend) {
;     ...
;                 PG8_LDB(B0, 1, 0); PG8_SCHED; PG8_LDA(At, 1, 0); PG8_STAGE2(PG8_SA(0, 1), a2 + h2, rA2, K2);
;                 PG8_WAIT_L(8); PG8_BAR; PG8_WAIT_L(0); PG8_MMA(0, 0, At, B0); PG8_BAR; PG8_SCHED;
;                 PG8_LDB(B1, 1, 1); PG8_STAGE2(PG8_SB(1, 0), b3, rB2, K2);
;                 PG8_BAR; PG8_WAIT_L(0); PG8_MMA(0, 1, At, B1); PG8_BAR;
;                 PG8_LDA(At, 1, 1); PG8_STAGE2(PG8_SA(1, 0), a3, rA2, K2);
;                 PG8_BAR; PG8_WAIT_L(0); PG8_MMA(1, 0, At, B0); PG8_BAR; PG8_SCHED;
	s_waitcnt lgkmcnt(0)
	v_mov_b32_e32 v227, v1
	v_lshl_add_u64 v[228:229], s[26:27], 0, v[224:225]
	v_lshl_add_u64 v[230:231], s[26:27], 0, v[226:227]
	s_setprio 1
	s_waitcnt lgkmcnt(0)
	v_mfma_f32_16x16x32_bf16 v[64:67], v[134:137], v[170:173], v[64:67]
	v_mfma_f32_16x16x32_bf16 v[60:63], v[142:145], v[170:173], v[60:63]
	v_mfma_f32_16x16x32_bf16 v[56:59], v[134:137], v[178:181], v[56:59]
	v_mfma_f32_16x16x32_bf16 v[52:55], v[142:145], v[178:181], v[52:55]
	v_mfma_f32_16x16x32_bf16 v[48:51], v[134:137], v[186:189], v[48:51]
	v_mfma_f32_16x16x32_bf16 v[44:47], v[142:145], v[186:189], v[44:47]
	v_mfma_f32_16x16x32_bf16 v[40:43], v[134:137], v[194:197], v[40:43]
	v_mfma_f32_16x16x32_bf16 v[36:39], v[142:145], v[194:197], v[36:39]
	v_mfma_f32_16x16x32_bf16 v[64:67], v[138:141], v[174:177], v[64:67]
	v_mfma_f32_16x16x32_bf16 v[60:63], v[146:149], v[174:177], v[60:63]
	v_mfma_f32_16x16x32_bf16 v[56:59], v[138:141], v[182:185], v[56:59]
	v_mfma_f32_16x16x32_bf16 v[52:55], v[146:149], v[182:185], v[52:55]
	v_mfma_f32_16x16x32_bf16 v[48:51], v[138:141], v[190:193], v[48:51]
	v_mfma_f32_16x16x32_bf16 v[44:47], v[146:149], v[190:193], v[44:47]
	v_mfma_f32_16x16x32_bf16 v[40:43], v[138:141], v[198:201], v[40:43]
	v_mfma_f32_16x16x32_bf16 v[36:39], v[146:149], v[198:201], v[36:39]
	s_setprio 0
	s_barrier
	s_add_u32 s28, s28, s66
	s_addc_u32 s29, s29, s63
	s_add_i32 s64, s49, s33
	s_mov_b32 m0, s64
	v_lshl_add_u64 v[232:233], s[28:29], 0, v[0:1]
	global_load_lds_dwordx4 v0, s[28:29]
	s_add_i32 m0, s64, 0x2000
	s_nop 0
	global_load_lds_dwordx4 v150, s[28:29]
	s_waitcnt vmcnt(6)
	v_lshl_add_u64 v[150:151], s[28:29], 0, v[150:151]
	s_barrier
	s_setprio 1
	v_mfma_f32_16x16x32_bf16 v[32:35], v[202:205], v[170:173], v[32:35]
	v_mfma_f32_16x16x32_bf16 v[28:31], v[214:217], v[170:173], v[28:31]
	v_mfma_f32_16x16x32_bf16 v[24:27], v[202:205], v[178:181], v[24:27]
	v_mfma_f32_16x16x32_bf16 v[20:23], v[214:217], v[178:181], v[20:23]
	v_mfma_f32_16x16x32_bf16 v[16:19], v[202:205], v[186:189], v[16:19]
	v_mfma_f32_16x16x32_bf16 v[12:15], v[214:217], v[186:189], v[12:15]
	v_mfma_f32_16x16x32_bf16 v[8:11], v[202:205], v[194:197], v[8:11]
	v_mfma_f32_16x16x32_bf16 v[4:7], v[214:217], v[194:197], v[4:7]
	v_mfma_f32_16x16x32_bf16 v[32:35], v[206:209], v[174:177], v[32:35]
	v_mfma_f32_16x16x32_bf16 v[28:31], v[218:221], v[174:177], v[28:31]
	v_mfma_f32_16x16x32_bf16 v[24:27], v[206:209], v[182:185], v[24:27]
	v_mfma_f32_16x16x32_bf16 v[20:23], v[218:221], v[182:185], v[20:23]
	v_mfma_f32_16x16x32_bf16 v[16:19], v[206:209], v[190:193], v[16:19]
	v_mfma_f32_16x16x32_bf16 v[12:15], v[218:221], v[190:193], v[12:15]
	v_mfma_f32_16x16x32_bf16 v[8:11], v[206:209], v[198:201], v[8:11]
	v_mfma_f32_16x16x32_bf16 v[4:7], v[218:221], v[198:201], v[4:7]
	s_setprio 0
	s_add_i32 s28, 0, 0x18000
	v_add_u32_e32 v0, s28, v159
	s_barrier
	ds_read_b128 v[134:137], v0
	ds_read_b128 v[138:141], v0 offset:1024
	ds_read_b128 v[142:145], v0 offset:2048
	ds_read_b128 v[146:149], v0 offset:3072
	s_add_u32 s26, s26, s66
	s_addc_u32 s27, s27, s63
	s_mov_b32 m0, s38
	ds_read_b128 v[170:173], v165 offset:32768
	ds_read_b128 v[174:177], v165 offset:33792
	ds_read_b128 v[178:181], v165 offset:34816
	ds_read_b128 v[182:185], v165 offset:35840
	ds_read_b128 v[186:189], v165 offset:36864
	ds_read_b128 v[190:193], v165 offset:37888
	ds_read_b128 v[194:197], v165 offset:38912
	ds_read_b128 v[198:201], v165 offset:39936
	global_load_lds_dwordx4 v224, s[26:27]
	s_mov_b32 m0, s39
	s_nop 0
	global_load_lds_dwordx4 v226, s[26:27]
	s_waitcnt lgkmcnt(8)
	s_barrier
	s_waitcnt lgkmcnt(0)
	s_setprio 1
	s_waitcnt lgkmcnt(0)
	v_mfma_f32_16x16x32_bf16 v[128:131], v[134:137], v[170:173], v[128:131]
	v_mfma_f32_16x16x32_bf16 v[124:127], v[142:145], v[170:173], v[124:127]
	v_mfma_f32_16x16x32_bf16 v[120:123], v[134:137], v[178:181], v[120:123]
	v_mfma_f32_16x16x32_bf16 v[116:119], v[142:145], v[178:181], v[116:119]
	v_mfma_f32_16x16x32_bf16 v[112:115], v[134:137], v[186:189], v[112:115]
	v_mfma_f32_16x16x32_bf16 v[108:111], v[142:145], v[186:189], v[108:111]
	v_mfma_f32_16x16x32_bf16 v[104:107], v[134:137], v[194:197], v[104:107]
	v_mfma_f32_16x16x32_bf16 v[100:103], v[142:145], v[194:197], v[100:103]
	v_mfma_f32_16x16x32_bf16 v[128:131], v[138:141], v[174:177], v[128:131]
	v_mfma_f32_16x16x32_bf16 v[124:127], v[146:149], v[174:177], v[124:127]
	v_mfma_f32_16x16x32_bf16 v[120:123], v[138:141], v[182:185], v[120:123]
	v_mfma_f32_16x16x32_bf16 v[116:119], v[146:149], v[182:185], v[116:119]
	v_mfma_f32_16x16x32_bf16 v[112:115], v[138:141], v[190:193], v[112:115]
	v_mfma_f32_16x16x32_bf16 v[108:111], v[146:149], v[190:193], v[108:111]
	v_mfma_f32_16x16x32_bf16 v[104:107], v[138:141], v[198:201], v[104:107]
	v_mfma_f32_16x16x32_bf16 v[100:103], v[146:149], v[198:201], v[100:103]
	s_setprio 0
	s_barrier
	s_add_i32 s26, 0, 0x1c000
	s_add_i32 s27, s28, s33
	v_add_u32_e32 v0, s26, v159
	v_lshl_add_u64 v[210:211], v[210:211], 0, s[8:9]
	s_mov_b32 m0, s27
	ds_read_b128 v[202:205], v0
	ds_read_b128 v[206:209], v0 offset:1024
	ds_read_b128 v[214:217], v0 offset:2048
	ds_read_b128 v[218:221], v0 offset:3072
	global_load_lds_dwordx4 v[210:211], off
	v_lshl_add_u64 v[210:211], v[222:223], 0, s[8:9]
	s_add_i32 m0, s27, 0x2000
	s_nop 0
	global_load_lds_dwordx4 v[210:211], off
	s_barrier
; #define PG8_LDA(dst, b, h) do { _Pragma("unroll") for (int m = 0; m < 4; ++m) _Pragma("unroll") for (int k = 0; k < 2; ++k) dst[m][k] = *(const LAS bf16x8*)(lds + PG8_SA(b, h) + aoff + m * 2048 + k * 1024); } while (0)
; #define PG8_MMA(ai, bj, At, Bt) do { __builtin_amdgcn_s_setprio(1); _Pragma("unroll") for (int m = 0; m < 4; ++m) _Pragma("unroll") for (int n = 0; n < 2; ++n) _Pragma("unroll") for (int k = 0; k < 2; ++k) \
;         acc[ai][bj][m][n] = __builtin_amdgcn_mfma_f32_16x16x32_bf16(Bt[n][k], At[m][k], acc[ai][bj][m][n], 0, 0, 0); __builtin_amdgcn_s_setprio(0); } while (0)
; #define PG8_WAIT_V(n) asm volatile("s_waitcnt vmcnt(" #n ")" ::: "memory")
; #define PG8_WAIT_L(n) asm volatile("s_waitcnt lgkmcnt(" #n ")" ::: "memory")
; #define PG8_BAR __builtin_amdgcn_s_barrier()
; #define PG8_SCHED __builtin_amdgcn_sched_barrier(0)
; #define PG8_STAGE2(bufoff, gbase, r2, Ksel) do { \
;         __builtin_amdgcn_global_load_lds((const unsigned*)((const char*)(gbase) + ((r2)[0] * (Ksel) + cb2[0])), (LAS unsigned*)(lds + (bufoff) + ldsw), 16, 0, 0); \
;         __builtin_amdgcn_global_load_lds((const unsigned*)((const char*)(gbase) + ((r2)[1] * (Ksel) + cb2[1])), (LAS unsigned*)(lds + (bufoff) + ldsw + 8192), 16, 0, 0); } while (0)
; #define PG8_LDA(dst, b, h) do { _Pragma("unroll") for (int m = 0; m < 4; ++m) _Pragma("unroll") for (int k = 0; k < 2; ++k) dst[m][k] = *(const LAS bf16x8*)(lds + PG8_SA(b, h) + aoff + m * 2048 + k * 1024); } while (0)
; #define PG8_WAIT_V(n) asm volatile("s_waitcnt vmcnt(" #n ")" ::: "memory")
; #define PG8_WAIT_L(n) asm volatile("s_waitcnt lgkmcnt(" #n ")" ::: "memory")
; #define PG8_BAR __builtin_amdgcn_s_barrier()
; #define PG8_SCHED __builtin_amdgcn_sched_barrier(0)
; template <class EpiMid, class EpiEnd>
; __device__ __forceinline__ void gemm_phase2(LAS unsigned char* lds, const Gemm g0, const Gemm g1, const StaticOrder& S, const EpiMid& Emid, const EpiEnd& Eend) {
;     ...
;                 PG8_LDA(At, 1, 1); PG8_STAGE2(PG8_SA(1, 0), a3, rA2, K2);
;                 PG8_BAR; PG8_WAIT_L(0); PG8_MMA(1, 0, At, B0); PG8_BAR; PG8_SCHED;
;                 PG8_STAGE2(PG8_SB(1, 1), b3 + h2, rB2, K2);
;                 PG8_WAIT_V(6); PG8_BAR; PG8_MMA(1, 1, At, B1); PG8_BAR;
;             }
;             if (seg == 0) Emid(acc, cur, wr, wc, fr, fq); else Eend(acc, cur, wr, wc, fr, fq);
;             cA = nA; cB = nB;
	s_waitcnt lgkmcnt(0)
	s_setprio 1
	s_waitcnt lgkmcnt(0)
	v_mfma_f32_16x16x32_bf16 v[96:99], v[202:205], v[170:173], v[96:99]
	v_mfma_f32_16x16x32_bf16 v[92:95], v[214:217], v[170:173], v[92:95]
	v_mfma_f32_16x16x32_bf16 v[88:91], v[202:205], v[178:181], v[88:91]
	v_mfma_f32_16x16x32_bf16 v[84:87], v[214:217], v[178:181], v[84:87]
	v_mfma_f32_16x16x32_bf16 v[80:83], v[202:205], v[186:189], v[80:83]
	v_mfma_f32_16x16x32_bf16 v[76:79], v[214:217], v[186:189], v[76:79]
	v_mfma_f32_16x16x32_bf16 v[72:75], v[202:205], v[194:197], v[72:75]
	v_mfma_f32_16x16x32_bf16 v[68:71], v[214:217], v[194:197], v[68:71]
	v_mfma_f32_16x16x32_bf16 v[96:99], v[206:209], v[174:177], v[96:99]
	v_mfma_f32_16x16x32_bf16 v[92:95], v[218:221], v[174:177], v[92:95]
	v_mfma_f32_16x16x32_bf16 v[88:91], v[206:209], v[182:185], v[88:91]
	v_mfma_f32_16x16x32_bf16 v[84:87], v[218:221], v[182:185], v[84:87]
	v_mfma_f32_16x16x32_bf16 v[80:83], v[206:209], v[190:193], v[80:83]
	v_mfma_f32_16x16x32_bf16 v[76:79], v[218:221], v[190:193], v[76:79]
	v_mfma_f32_16x16x32_bf16 v[72:75], v[206:209], v[198:201], v[72:75]
	v_mfma_f32_16x16x32_bf16 v[68:71], v[218:221], v[198:201], v[68:71]
	s_setprio 0
	s_mov_b32 m0, s43
	v_lshl_add_u64 v[210:211], v[228:229], 0, s[8:9]
	s_barrier
	ds_read_b128 v[170:173], v165 offset:49152
	ds_read_b128 v[174:177], v165 offset:50176
	ds_read_b128 v[178:181], v165 offset:51200
	ds_read_b128 v[182:185], v165 offset:52224
	ds_read_b128 v[186:189], v165 offset:53248
	ds_read_b128 v[190:193], v165 offset:54272
	ds_read_b128 v[194:197], v165 offset:55296
	ds_read_b128 v[198:201], v165 offset:56320
	global_load_lds_dwordx4 v[210:211], off
	v_lshl_add_u64 v[210:211], v[230:231], 0, s[8:9]
	s_mov_b32 m0, s44
	s_nop 0
	global_load_lds_dwordx4 v[210:211], off
	s_barrier
	s_waitcnt lgkmcnt(0)
	s_setprio 1
	s_waitcnt lgkmcnt(0)
	v_mfma_f32_16x16x32_bf16 v[64:67], v[134:137], v[170:173], v[64:67]
	v_mfma_f32_16x16x32_bf16 v[60:63], v[142:145], v[170:173], v[60:63]
	v_mfma_f32_16x16x32_bf16 v[56:59], v[134:137], v[178:181], v[56:59]
	v_mfma_f32_16x16x32_bf16 v[52:55], v[142:145], v[178:181], v[52:55]
	v_mfma_f32_16x16x32_bf16 v[48:51], v[134:137], v[186:189], v[48:51]
	v_mfma_f32_16x16x32_bf16 v[44:47], v[142:145], v[186:189], v[44:47]
	v_mfma_f32_16x16x32_bf16 v[40:43], v[134:137], v[194:197], v[40:43]
	v_mfma_f32_16x16x32_bf16 v[36:39], v[142:145], v[194:197], v[36:39]
	v_mfma_f32_16x16x32_bf16 v[64:67], v[138:141], v[174:177], v[64:67]
	v_mfma_f32_16x16x32_bf16 v[60:63], v[146:149], v[174:177], v[60:63]
	v_mfma_f32_16x16x32_bf16 v[56:59], v[138:141], v[182:185], v[56:59]
	v_mfma_f32_16x16x32_bf16 v[52:55], v[146:149], v[182:185], v[52:55]
	v_mfma_f32_16x16x32_bf16 v[48:51], v[138:141], v[190:193], v[48:51]
	v_mfma_f32_16x16x32_bf16 v[44:47], v[146:149], v[190:193], v[44:47]
	v_mfma_f32_16x16x32_bf16 v[40:43], v[138:141], v[198:201], v[40:43]
	v_mfma_f32_16x16x32_bf16 v[36:39], v[146:149], v[198:201], v[36:39]
	s_setprio 0
	s_barrier
	s_add_i32 s26, s26, s33
	v_lshl_add_u64 v[134:135], v[232:233], 0, s[8:9]
	s_mov_b32 m0, s26
	s_nop 0
	global_load_lds_dwordx4 v[134:135], off
	v_lshl_add_u64 v[134:135], v[150:151], 0, s[8:9]
	s_add_i32 m0, s26, 0x2000
	s_nop 0
	global_load_lds_dwordx4 v[134:135], off
	s_waitcnt vmcnt(6)
	s_barrier
	s_setprio 1
	v_mfma_f32_16x16x32_bf16 v[32:35], v[202:205], v[170:173], v[32:35]
	v_mfma_f32_16x16x32_bf16 v[28:31], v[214:217], v[170:173], v[28:31]
	v_mfma_f32_16x16x32_bf16 v[24:27], v[202:205], v[178:181], v[24:27]
	v_mfma_f32_16x16x32_bf16 v[20:23], v[214:217], v[178:181], v[20:23]
	v_mfma_f32_16x16x32_bf16 v[16:19], v[202:205], v[186:189], v[16:19]
	v_mfma_f32_16x16x32_bf16 v[12:15], v[214:217], v[186:189], v[12:15]
	v_mfma_f32_16x16x32_bf16 v[8:11], v[202:205], v[194:197], v[8:11]
	v_mfma_f32_16x16x32_bf16 v[4:7], v[214:217], v[194:197], v[4:7]
	v_mfma_f32_16x16x32_bf16 v[32:35], v[206:209], v[174:177], v[32:35]
	v_mfma_f32_16x16x32_bf16 v[28:31], v[218:221], v[174:177], v[28:31]
	v_mfma_f32_16x16x32_bf16 v[24:27], v[206:209], v[182:185], v[24:27]
	v_mfma_f32_16x16x32_bf16 v[20:23], v[218:221], v[182:185], v[20:23]
	v_mfma_f32_16x16x32_bf16 v[16:19], v[206:209], v[190:193], v[16:19]
	v_mfma_f32_16x16x32_bf16 v[12:15], v[218:221], v[190:193], v[12:15]
	v_mfma_f32_16x16x32_bf16 v[8:11], v[206:209], v[198:201], v[8:11]
	v_mfma_f32_16x16x32_bf16 v[4:7], v[218:221], v[198:201], v[4:7]
	s_setprio 0
	s_add_u32 s24, s24, 0x100
	s_addc_u32 s25, s25, 0
	s_cmp_ge_u32 s54, s52
	s_barrier
	s_cbranch_scc0 .LBB0_772
	s_mov_b64 s[20:21], -1
	s_and_b64 vcc, exec, s[18:19]
	s_cbranch_vccz .LBB0_775
; __device__ __forceinline__ float sigmoidf_(float x) { return __builtin_amdgcn_rcpf(1.0f + __expf(-x)); }
;     __device__ __forceinline__ void operator()(f32x4 (&acc)[2][2][4][2], const pg8::Unit& u, int wr, int wc, int fr, int fq) const {
;     ...
;         for (int ai = 0; ai < 2; ++ai) {
;             u32x4 ga[4][2];
; #pragma unroll
;             for (int m = 0; m < 4; ++m)
; #pragma unroll
;                 for (int bj = 0; bj < 2; ++bj) ga[m][bj] = __builtin_nontemporal_load((const u32x4*)((const char*)Gt + (goff + (unsigned)(ai * 128 + m * 16) * 4096u + 256u * bj)));
; #pragma unroll
;             for (int m = 0; m < 4; ++m) {
;                 const unsigned rm = moff + (unsigned)(ai * 128 + m * 16) * 2048u;
; #pragma unroll
;                 for (int bj = 0; bj < 2; ++bj) {
;                     float fa[8], o[8]; unpack8(ga[m][bj], fa);
; #pragma unroll
;                     for (int e = 0; e < 8; ++e) o[e] = sigmoidf_(fa[e]) * acc[ai][bj][m][e >> 2][e & 3];
;                     *(u32x4*)((char*)MG + (rm + 256u * bj)) = pack8(o);
;                 }
;             }
;             asm volatile("" ::: "memory");
;         }
	v_mov_b32_e32 v2, v166
	v_mov_b32_e32 v0, v167
	global_load_dwordx4 v[170:173], v2, s[94:95] nt
	v_add_u32_e32 v3, 0x100, v2
	global_load_dwordx4 v[174:177], v3, s[94:95] nt
	v_add_u32_e32 v3, 0x10000, v2
	v_add_u32_e32 v132, 0x10100, v2
	v_add_u32_e32 v133, 0x20000, v2
	v_add_u32_e32 v134, 0x20100, v2
	v_add_u32_e32 v135, 0x30000, v2
	v_add_u32_e32 v169, 0x30100, v2
	global_load_dwordx4 v[178:181], v3, s[94:95] nt
	global_load_dwordx4 v[148:151], v132, s[94:95] nt
	global_load_dwordx4 v[144:147], v133, s[94:95] nt
	global_load_dwordx4 v[140:143], v134, s[94:95] nt
	global_load_dwordx4 v[136:139], v135, s[94:95] nt
	s_nop 0
	global_load_dwordx4 v[132:135], v169, s[94:95] nt
	s_mov_b64 s[20:21], 0
	s_waitcnt vmcnt(0)
	v_lshlrev_b32_e32 v3, 16, v170
	v_and_b32_e32 v169, 0xffff0000, v170
	v_lshlrev_b32_e32 v170, 16, v171
	v_and_b32_e32 v171, 0xffff0000, v171
	v_lshlrev_b32_e32 v182, 16, v172
	v_and_b32_e32 v172, 0xffff0000, v172
	v_lshlrev_b32_e32 v183, 16, v173
	v_and_b32_e32 v173, 0xffff0000, v173
	v_mul_f32_e32 v3, 0xbfb8aa3b, v3
	v_mul_f32_e32 v169, 0xbfb8aa3b, v169
	v_mul_f32_e32 v170, 0xbfb8aa3b, v170
	v_mul_f32_e32 v171, 0xbfb8aa3b, v171
	v_mul_f32_e32 v182, 0xbfb8aa3b, v182
	v_mul_f32_e32 v172, 0xbfb8aa3b, v172
	v_mul_f32_e32 v183, 0xbfb8aa3b, v183
	v_mul_f32_e32 v173, 0xbfb8aa3b, v173
	v_lshlrev_b32_e32 v187, 16, v177
	v_and_b32_e32 v188, 0xffff0000, v177
	v_exp_f32_e32 v3, v3
	v_exp_f32_e32 v169, v169
	v_exp_f32_e32 v170, v170
	v_exp_f32_e32 v171, v171
	v_exp_f32_e32 v177, v182
	v_exp_f32_e32 v172, v172
	v_exp_f32_e32 v182, v183
	v_exp_f32_e32 v173, v173
	v_lshlrev_b32_e32 v184, 16, v174
	v_and_b32_e32 v174, 0xffff0000, v174
	v_lshlrev_b32_e32 v185, 16, v175
	v_and_b32_e32 v175, 0xffff0000, v175
	v_lshlrev_b32_e32 v186, 16, v176
	v_and_b32_e32 v176, 0xffff0000, v176
	v_mul_f32_e32 v174, 0xbfb8aa3b, v174
	v_mul_f32_e32 v175, 0xbfb8aa3b, v175
	v_mul_f32_e32 v176, 0xbfb8aa3b, v176
	v_mul_f32_e32 v183, 0xbfb8aa3b, v184
	v_mul_f32_e32 v184, 0xbfb8aa3b, v185
	v_mul_f32_e32 v185, 0xbfb8aa3b, v186
	v_exp_f32_e32 v186, v174
	v_exp_f32_e32 v189, v175
	v_exp_f32_e32 v190, v176
	v_add_f32_e32 v3, 1.0, v3
	v_add_f32_e32 v169, 1.0, v169
	v_add_f32_e32 v174, 1.0, v170
	v_add_f32_e32 v175, 1.0, v171
	v_add_f32_e32 v176, 1.0, v177
	v_add_f32_e32 v177, 1.0, v172
	v_add_f32_e32 v182, 1.0, v182
	v_add_f32_e32 v191, 1.0, v173
	v_rcp_f32_e32 v170, v3
	v_rcp_f32_e32 v171, v169
	v_rcp_f32_e32 v172, v174
	v_rcp_f32_e32 v173, v175
	v_rcp_f32_e32 v174, v176
	v_rcp_f32_e32 v175, v177
	v_rcp_f32_e32 v176, v182
	v_rcp_f32_e32 v177, v191
	v_exp_f32_e32 v183, v183
	v_add_f32_e32 v169, 1.0, v186
	v_pk_mul_f32 v[170:171], v[128:129], v[170:171]
	v_pk_mul_f32 v[172:173], v[130:131], v[172:173]
	v_pk_mul_f32 v[174:175], v[124:125], v[174:175]
	v_pk_mul_f32 v[176:177], v[126:127], v[176:177]
	v_add_f32_e32 v3, 1.0, v183
	v_rcp_f32_e32 v183, v169
	v_cvt_pk_bf16_f32 v170, v170, v171
	v_cvt_pk_bf16_f32 v171, v172, v173
	v_cvt_pk_bf16_f32 v172, v174, v175
	v_cvt_pk_bf16_f32 v173, v176, v177
	v_mul_f32_e32 v169, 0xbfb8aa3b, v187
	global_store_dwordx4 v0, v[170:173], s[4:5]
	v_exp_f32_e32 v169, v169
	v_exp_f32_e32 v184, v184
	v_mul_f32_e32 v171, 0xbfb8aa3b, v188
	v_exp_f32_e32 v185, v185
	v_exp_f32_e32 v173, v171
	v_rcp_f32_e32 v182, v3
	v_add_f32_e32 v3, 1.0, v190
	v_rcp_f32_e32 v171, v3
	v_add_f32_e32 v3, 1.0, v169
	v_add_f32_e32 v184, 1.0, v184
	v_add_f32_e32 v186, 1.0, v189
	v_add_f32_e32 v189, 1.0, v185
	v_rcp_f32_e32 v172, v3
	v_add_f32_e32 v3, 1.0, v173
	v_rcp_f32_e32 v184, v184
	v_rcp_f32_e32 v185, v186
	v_rcp_f32_e32 v170, v189
	v_rcp_f32_e32 v173, v3
	v_pk_mul_f32 v[174:175], v[96:97], v[182:183]
	v_pk_mul_f32 v[176:177], v[98:99], v[184:185]
	v_pk_mul_f32 v[182:183], v[92:93], v[170:171]
	v_pk_mul_f32 v[184:185], v[94:95], v[172:173]
	v_cvt_pk_bf16_f32 v170, v174, v175
	v_cvt_pk_bf16_f32 v171, v176, v177
	v_cvt_pk_bf16_f32 v172, v182, v183
	v_cvt_pk_bf16_f32 v173, v184, v185
	v_add_u32_e32 v3, 0x100, v0
	v_lshlrev_b32_e32 v169, 16, v178
	global_store_dwordx4 v3, v[170:173], s[4:5]
	v_mul_f32_e32 v169, 0xbfb8aa3b, v169
	v_exp_f32_e32 v169, v169
	v_and_b32_e32 v170, 0xffff0000, v178
	v_mul_f32_e32 v170, 0xbfb8aa3b, v170
	v_exp_f32_e32 v176, v170
	v_lshlrev_b32_e32 v171, 16, v179
	v_add_f32_e32 v169, 1.0, v169
	v_mul_f32_e32 v171, 0xbfb8aa3b, v171
	v_rcp_f32_e32 v170, v169
	v_add_f32_e32 v169, 1.0, v176
	v_exp_f32_e32 v176, v171
	v_and_b32_e32 v172, 0xffff0000, v179
	v_lshlrev_b32_e32 v173, 16, v180
	v_mul_f32_e32 v171, 0xbfb8aa3b, v172
	v_exp_f32_e32 v178, v171
	v_mul_f32_e32 v173, 0xbfb8aa3b, v173
	v_rcp_f32_e32 v171, v169
	v_add_f32_e32 v169, 1.0, v176
	v_exp_f32_e32 v176, v173
	v_and_b32_e32 v174, 0xffff0000, v180
	v_lshlrev_b32_e32 v175, 16, v181
	v_mul_f32_e32 v173, 0xbfb8aa3b, v174
	v_and_b32_e32 v177, 0xffff0000, v181
	v_rcp_f32_e32 v172, v169
	v_add_f32_e32 v169, 1.0, v178
	v_exp_f32_e32 v178, v173
	v_mul_f32_e32 v175, 0xbfb8aa3b, v175
	v_rcp_f32_e32 v173, v169
	v_add_f32_e32 v169, 1.0, v176
	v_exp_f32_e32 v176, v175
	v_mul_f32_e32 v175, 0xbfb8aa3b, v177
	v_exp_f32_e32 v177, v175
	v_rcp_f32_e32 v174, v169
	v_add_f32_e32 v169, 1.0, v178
	v_rcp_f32_e32 v175, v169
	v_add_f32_e32 v169, 1.0, v176
	v_rcp_f32_e32 v176, v169
	v_add_f32_e32 v169, 1.0, v177
	v_rcp_f32_e32 v177, v169
	v_pk_mul_f32 v[170:171], v[120:121], v[170:171]
	v_pk_mul_f32 v[172:173], v[122:123], v[172:173]
	v_pk_mul_f32 v[174:175], v[116:117], v[174:175]
	v_pk_mul_f32 v[176:177], v[118:119], v[176:177]
	v_add_u32_e32 v3, 0x8000, v0
	v_cvt_pk_bf16_f32 v170, v170, v171
	v_cvt_pk_bf16_f32 v171, v172, v173
	v_cvt_pk_bf16_f32 v172, v174, v175
	v_cvt_pk_bf16_f32 v173, v176, v177
; __device__ __forceinline__ float sigmoidf_(float x) { return __builtin_amdgcn_rcpf(1.0f + __expf(-x)); }
;     __device__ __forceinline__ void operator()(f32x4 (&acc)[2][2][4][2], const pg8::Unit& u, int wr, int wc, int fr, int fq) const {
;     ...
;         for (int ai = 0; ai < 2; ++ai) {
;             u32x4 ga[4][2];
; #pragma unroll
;             for (int m = 0; m < 4; ++m)
; #pragma unroll
;                 for (int bj = 0; bj < 2; ++bj) ga[m][bj] = __builtin_nontemporal_load((const u32x4*)((const char*)Gt + (goff + (unsigned)(ai * 128 + m * 16) * 4096u + 256u * bj)));
; #pragma unroll
;             for (int m = 0; m < 4; ++m) {
;                 const unsigned rm = moff + (unsigned)(ai * 128 + m * 16) * 2048u;
; #pragma unroll
;                 for (int bj = 0; bj < 2; ++bj) {
;                     float fa[8], o[8]; unpack8(ga[m][bj], fa);
; #pragma unroll
;                     for (int e = 0; e < 8; ++e) o[e] = sigmoidf_(fa[e]) * acc[ai][bj][m][e >> 2][e & 3];
;                     *(u32x4*)((char*)MG + (rm + 256u * bj)) = pack8(o);
;                 }
;             }
;             asm volatile("" ::: "memory");
;         }
	global_store_dwordx4 v3, v[170:173], s[4:5]
	v_lshlrev_b32_e32 v3, 16, v148
	v_and_b32_e32 v148, 0xffff0000, v148
	v_mul_f32_e32 v3, 0xbfb8aa3b, v3
	v_exp_f32_e32 v3, v3
	v_mul_f32_e32 v148, 0xbfb8aa3b, v148
	v_lshlrev_b32_e32 v170, 16, v150
	v_and_b32_e32 v171, 0xffff0000, v150
	v_exp_f32_e32 v150, v148
	v_lshlrev_b32_e32 v169, 16, v149
	v_add_f32_e32 v3, 1.0, v3
	v_and_b32_e32 v149, 0xffff0000, v149
	v_rcp_f32_e32 v148, v3
	v_add_f32_e32 v3, 1.0, v150
	v_mul_f32_e32 v150, 0xbfb8aa3b, v169
	v_exp_f32_e32 v150, v150
	v_mul_f32_e32 v149, 0xbfb8aa3b, v149
	v_lshlrev_b32_e32 v172, 16, v151
	v_and_b32_e32 v173, 0xffff0000, v151
	v_exp_f32_e32 v151, v149
	v_rcp_f32_e32 v149, v3
	v_add_f32_e32 v3, 1.0, v150
	v_rcp_f32_e32 v150, v3
	v_add_f32_e32 v3, 1.0, v151
	v_mul_f32_e32 v151, 0xbfb8aa3b, v170
	v_exp_f32_e32 v169, v151
	v_mul_f32_e32 v151, 0xbfb8aa3b, v171
	v_exp_f32_e32 v171, v151
	v_rcp_f32_e32 v151, v3
	v_add_f32_e32 v3, 1.0, v169
	v_mul_f32_e32 v169, 0xbfb8aa3b, v172
	v_rcp_f32_e32 v170, v3
	v_add_f32_e32 v3, 1.0, v171
	v_exp_f32_e32 v169, v169
	v_mul_f32_e32 v171, 0xbfb8aa3b, v173
	v_exp_f32_e32 v173, v171
	v_rcp_f32_e32 v171, v3
	v_add_f32_e32 v3, 1.0, v169
	v_rcp_f32_e32 v172, v3
	v_add_f32_e32 v3, 1.0, v173
	v_rcp_f32_e32 v173, v3
	v_pk_mul_f32 v[148:149], v[88:89], v[148:149]
	v_pk_mul_f32 v[150:151], v[90:91], v[150:151]
	v_pk_mul_f32 v[170:171], v[84:85], v[170:171]
	v_pk_mul_f32 v[172:173], v[86:87], v[172:173]
	v_cvt_pk_bf16_f32 v148, v148, v149
	v_cvt_pk_bf16_f32 v149, v150, v151
	v_cvt_pk_bf16_f32 v150, v170, v171
	v_cvt_pk_bf16_f32 v151, v172, v173
	v_add_u32_e32 v3, 0x8100, v0
	global_store_dwordx4 v3, v[148:151], s[4:5]
	v_lshlrev_b32_e32 v169, 16, v147
	v_and_b32_e32 v170, 0xffff0000, v147
	v_lshlrev_b32_e32 v148, 16, v144
	v_and_b32_e32 v144, 0xffff0000, v144
	v_lshlrev_b32_e32 v150, 16, v146
	v_and_b32_e32 v151, 0xffff0000, v146
	v_mul_f32_e32 v146, 0xbfb8aa3b, v148
	v_mul_f32_e32 v144, 0xbfb8aa3b, v144
	v_exp_f32_e32 v146, v146
	v_exp_f32_e32 v148, v144
	v_lshlrev_b32_e32 v149, 16, v145
	v_and_b32_e32 v145, 0xffff0000, v145
	v_mul_f32_e32 v147, 0xbfb8aa3b, v149
	v_mul_f32_e32 v145, 0xbfb8aa3b, v145
	v_add_f32_e32 v144, 1.0, v146
	v_add_f32_e32 v146, 1.0, v148
	v_exp_f32_e32 v147, v147
	v_exp_f32_e32 v148, v145
	v_rcp_f32_e32 v145, v146
	v_mul_f32_e32 v149, 0xbfb8aa3b, v151
	v_add_f32_e32 v146, 1.0, v147
	v_add_f32_e32 v147, 1.0, v148
	v_mul_f32_e32 v148, 0xbfb8aa3b, v150
	v_mul_f32_e32 v150, 0xbfb8aa3b, v169
	v_mul_f32_e32 v151, 0xbfb8aa3b, v170
	v_exp_f32_e32 v148, v148
	v_exp_f32_e32 v149, v149
	v_exp_f32_e32 v150, v150
	v_exp_f32_e32 v151, v151
	v_add_f32_e32 v148, 1.0, v148
	v_add_f32_e32 v149, 1.0, v149
	v_add_f32_e32 v150, 1.0, v150
	v_add_f32_e32 v151, 1.0, v151
	v_rcp_f32_e32 v144, v144
	v_rcp_f32_e32 v146, v146
	v_rcp_f32_e32 v147, v147
	v_rcp_f32_e32 v148, v148
	v_rcp_f32_e32 v149, v149
	v_rcp_f32_e32 v150, v150
	v_rcp_f32_e32 v151, v151
	v_pk_mul_f32 v[144:145], v[112:113], v[144:145]
	v_pk_mul_f32 v[146:147], v[114:115], v[146:147]
	v_pk_mul_f32 v[148:149], v[108:109], v[148:149]
	v_pk_mul_f32 v[150:151], v[110:111], v[150:151]
	v_add_u32_e32 v3, 0x10000, v0
	v_cvt_pk_bf16_f32 v144, v144, v145
	v_cvt_pk_bf16_f32 v145, v146, v147
	v_cvt_pk_bf16_f32 v146, v148, v149
	v_cvt_pk_bf16_f32 v147, v150, v151
	global_store_dwordx4 v3, v[144:147], s[4:5]
	v_lshlrev_b32_e32 v3, 16, v140
	v_and_b32_e32 v140, 0xffff0000, v140
	v_mul_f32_e32 v3, 0xbfb8aa3b, v3
	v_exp_f32_e32 v3, v3
	v_mul_f32_e32 v140, 0xbfb8aa3b, v140
	v_lshlrev_b32_e32 v145, 16, v142
	v_and_b32_e32 v146, 0xffff0000, v142
	v_exp_f32_e32 v142, v140
	v_lshlrev_b32_e32 v144, 16, v141
	v_add_f32_e32 v3, 1.0, v3
	v_and_b32_e32 v141, 0xffff0000, v141
	v_rcp_f32_e32 v140, v3
	v_add_f32_e32 v3, 1.0, v142
	v_mul_f32_e32 v142, 0xbfb8aa3b, v144
	v_exp_f32_e32 v142, v142
	v_mul_f32_e32 v141, 0xbfb8aa3b, v141
	v_lshlrev_b32_e32 v147, 16, v143
	v_and_b32_e32 v148, 0xffff0000, v143
	v_exp_f32_e32 v143, v141
	v_rcp_f32_e32 v141, v3
	v_add_f32_e32 v3, 1.0, v142
	v_rcp_f32_e32 v142, v3
	v_add_f32_e32 v3, 1.0, v143
	v_mul_f32_e32 v143, 0xbfb8aa3b, v145
	v_exp_f32_e32 v144, v143
	v_mul_f32_e32 v143, 0xbfb8aa3b, v146
	v_exp_f32_e32 v145, v143
	v_rcp_f32_e32 v143, v3
	v_add_f32_e32 v3, 1.0, v144
	v_rcp_f32_e32 v144, v3
	v_add_f32_e32 v3, 1.0, v145
	v_mul_f32_e32 v145, 0xbfb8aa3b, v147
	v_exp_f32_e32 v146, v145
	v_mul_f32_e32 v145, 0xbfb8aa3b, v148
	v_exp_f32_e32 v147, v145
	v_rcp_f32_e32 v145, v3
	v_add_f32_e32 v3, 1.0, v146
	v_rcp_f32_e32 v146, v3
	v_add_f32_e32 v3, 1.0, v147
	v_rcp_f32_e32 v147, v3
	v_pk_mul_f32 v[140:141], v[80:81], v[140:141]
	v_pk_mul_f32 v[142:143], v[82:83], v[142:143]
	v_pk_mul_f32 v[144:145], v[76:77], v[144:145]
	v_pk_mul_f32 v[146:147], v[78:79], v[146:147]
	v_cvt_pk_bf16_f32 v140, v140, v141
	v_cvt_pk_bf16_f32 v141, v142, v143
	v_cvt_pk_bf16_f32 v142, v144, v145
	v_cvt_pk_bf16_f32 v143, v146, v147
	v_add_u32_e32 v3, 0x10100, v0
	global_store_dwordx4 v3, v[140:143], s[4:5]
	v_lshlrev_b32_e32 v144, 16, v139
	v_and_b32_e32 v145, 0xffff0000, v139
	v_lshlrev_b32_e32 v140, 16, v136
	v_and_b32_e32 v136, 0xffff0000, v136
	v_lshlrev_b32_e32 v142, 16, v138
	v_and_b32_e32 v143, 0xffff0000, v138
	v_mul_f32_e32 v138, 0xbfb8aa3b, v140
	v_mul_f32_e32 v136, 0xbfb8aa3b, v136
	v_exp_f32_e32 v138, v138
	v_exp_f32_e32 v140, v136
	v_lshlrev_b32_e32 v141, 16, v137
	v_and_b32_e32 v137, 0xffff0000, v137
	v_mul_f32_e32 v139, 0xbfb8aa3b, v141
	v_mul_f32_e32 v137, 0xbfb8aa3b, v137
	v_add_f32_e32 v136, 1.0, v138
	v_add_f32_e32 v138, 1.0, v140
	v_exp_f32_e32 v139, v139
	v_exp_f32_e32 v140, v137
	v_rcp_f32_e32 v137, v138
	v_mul_f32_e32 v141, 0xbfb8aa3b, v143
; __device__ __forceinline__ float sigmoidf_(float x) { return __builtin_amdgcn_rcpf(1.0f + __expf(-x)); }
;     __device__ __forceinline__ void operator()(f32x4 (&acc)[2][2][4][2], const pg8::Unit& u, int wr, int wc, int fr, int fq) const {
;     ...
;         for (int ai = 0; ai < 2; ++ai) {
;             u32x4 ga[4][2];
; #pragma unroll
;             for (int m = 0; m < 4; ++m)
; #pragma unroll
;                 for (int bj = 0; bj < 2; ++bj) ga[m][bj] = __builtin_nontemporal_load((const u32x4*)((const char*)Gt + (goff + (unsigned)(ai * 128 + m * 16) * 4096u + 256u * bj)));
; #pragma unroll
;             for (int m = 0; m < 4; ++m) {
;                 const unsigned rm = moff + (unsigned)(ai * 128 + m * 16) * 2048u;
; #pragma unroll
;                 for (int bj = 0; bj < 2; ++bj) {
;                     float fa[8], o[8]; unpack8(ga[m][bj], fa);
; #pragma unroll
;                     for (int e = 0; e < 8; ++e) o[e] = sigmoidf_(fa[e]) * acc[ai][bj][m][e >> 2][e & 3];
;                     *(u32x4*)((char*)MG + (rm + 256u * bj)) = pack8(o);
;                 }
;             }
;             asm volatile("" ::: "memory");
;         }
	v_add_f32_e32 v138, 1.0, v139
	v_add_f32_e32 v139, 1.0, v140
	v_mul_f32_e32 v140, 0xbfb8aa3b, v142
	v_mul_f32_e32 v142, 0xbfb8aa3b, v144
	v_mul_f32_e32 v143, 0xbfb8aa3b, v145
	v_exp_f32_e32 v140, v140
	v_exp_f32_e32 v141, v141
	v_exp_f32_e32 v142, v142
	v_exp_f32_e32 v143, v143
	v_add_f32_e32 v140, 1.0, v140
	v_add_f32_e32 v141, 1.0, v141
	v_add_f32_e32 v142, 1.0, v142
	v_add_f32_e32 v143, 1.0, v143
	v_rcp_f32_e32 v136, v136
	v_rcp_f32_e32 v138, v138
	v_rcp_f32_e32 v139, v139
	v_rcp_f32_e32 v140, v140
	v_rcp_f32_e32 v141, v141
	v_rcp_f32_e32 v142, v142
	v_rcp_f32_e32 v143, v143
	v_pk_mul_f32 v[136:137], v[104:105], v[136:137]
	v_pk_mul_f32 v[138:139], v[106:107], v[138:139]
	v_pk_mul_f32 v[140:141], v[100:101], v[140:141]
	v_pk_mul_f32 v[142:143], v[102:103], v[142:143]
	v_add_u32_e32 v3, 0x18000, v0
	v_cvt_pk_bf16_f32 v136, v136, v137
	v_cvt_pk_bf16_f32 v137, v138, v139
	v_cvt_pk_bf16_f32 v138, v140, v141
	v_cvt_pk_bf16_f32 v139, v142, v143
	global_store_dwordx4 v3, v[136:139], s[4:5]
	v_lshlrev_b32_e32 v3, 16, v132
	v_and_b32_e32 v132, 0xffff0000, v132
	v_mul_f32_e32 v3, 0xbfb8aa3b, v3
	v_exp_f32_e32 v3, v3
	v_mul_f32_e32 v132, 0xbfb8aa3b, v132
	v_lshlrev_b32_e32 v137, 16, v134
	v_and_b32_e32 v138, 0xffff0000, v134
	v_exp_f32_e32 v134, v132
	v_lshlrev_b32_e32 v136, 16, v133
	v_add_f32_e32 v3, 1.0, v3
	v_and_b32_e32 v133, 0xffff0000, v133
	v_rcp_f32_e32 v132, v3
	v_add_f32_e32 v3, 1.0, v134
	v_mul_f32_e32 v134, 0xbfb8aa3b, v136
	v_exp_f32_e32 v134, v134
	v_mul_f32_e32 v133, 0xbfb8aa3b, v133
	v_lshlrev_b32_e32 v139, 16, v135
	v_and_b32_e32 v140, 0xffff0000, v135
	v_exp_f32_e32 v135, v133
	v_rcp_f32_e32 v133, v3
	v_add_f32_e32 v3, 1.0, v134
	v_rcp_f32_e32 v134, v3
	v_add_f32_e32 v3, 1.0, v135
	v_mul_f32_e32 v135, 0xbfb8aa3b, v137
	v_exp_f32_e32 v136, v135
	v_mul_f32_e32 v135, 0xbfb8aa3b, v138
	v_exp_f32_e32 v137, v135
	v_rcp_f32_e32 v135, v3
	v_add_f32_e32 v3, 1.0, v136
	v_rcp_f32_e32 v136, v3
	v_add_f32_e32 v3, 1.0, v137
	v_mul_f32_e32 v137, 0xbfb8aa3b, v139
	v_exp_f32_e32 v138, v137
	v_mul_f32_e32 v137, 0xbfb8aa3b, v140
	v_exp_f32_e32 v139, v137
	v_rcp_f32_e32 v137, v3
	v_add_f32_e32 v3, 1.0, v138
	v_rcp_f32_e32 v138, v3
	v_add_f32_e32 v3, 1.0, v139
	v_rcp_f32_e32 v139, v3
	v_pk_mul_f32 v[132:133], v[72:73], v[132:133]
	v_pk_mul_f32 v[134:135], v[74:75], v[134:135]
	v_pk_mul_f32 v[136:137], v[68:69], v[136:137]
	v_pk_mul_f32 v[138:139], v[70:71], v[138:139]
	v_cvt_pk_bf16_f32 v132, v132, v133
	v_cvt_pk_bf16_f32 v133, v134, v135
	v_cvt_pk_bf16_f32 v134, v136, v137
	v_cvt_pk_bf16_f32 v135, v138, v139
	v_add_u32_e32 v3, 0x18100, v0
	global_store_dwordx4 v3, v[132:135], s[4:5]
	v_add_u32_e32 v3, 0x80000, v2
	global_load_dwordx4 v[170:173], v3, s[94:95] nt
	v_add_u32_e32 v3, 0x80100, v2
	global_load_dwordx4 v[174:177], v3, s[94:95] nt
	v_add_u32_e32 v3, 0x90000, v2
	v_add_u32_e32 v132, 0x90100, v2
	global_load_dwordx4 v[178:181], v3, s[94:95] nt
	global_load_dwordx4 v[148:151], v132, s[94:95] nt
	v_add_u32_e32 v3, 0xa0000, v2
	v_add_u32_e32 v132, 0xa0100, v2
	global_load_dwordx4 v[144:147], v3, s[94:95] nt
	global_load_dwordx4 v[140:143], v132, s[94:95] nt
	v_add_u32_e32 v3, 0xb0000, v2
	v_add_u32_e32 v2, 0xb0100, v2
	global_load_dwordx4 v[136:139], v3, s[94:95] nt
	global_load_dwordx4 v[132:135], v2, s[94:95] nt
	v_add_u32_e32 v169, 0x40000, v0
	s_waitcnt vmcnt(0)
	v_lshlrev_b32_e32 v182, 16, v172
	v_and_b32_e32 v172, 0xffff0000, v172
	v_mul_f32_e32 v182, 0xbfb8aa3b, v182
	v_mul_f32_e32 v172, 0xbfb8aa3b, v172
	v_exp_f32_e32 v182, v182
	v_exp_f32_e32 v184, v172
	v_lshlrev_b32_e32 v2, 16, v170
	v_and_b32_e32 v3, 0xffff0000, v170
	v_lshlrev_b32_e32 v170, 16, v171
	v_and_b32_e32 v171, 0xffff0000, v171
	v_lshlrev_b32_e32 v183, 16, v173
	v_and_b32_e32 v173, 0xffff0000, v173
	v_mul_f32_e32 v2, 0xbfb8aa3b, v2
	v_mul_f32_e32 v3, 0xbfb8aa3b, v3
	v_mul_f32_e32 v170, 0xbfb8aa3b, v170
	v_mul_f32_e32 v171, 0xbfb8aa3b, v171
	v_mul_f32_e32 v183, 0xbfb8aa3b, v183
	v_mul_f32_e32 v173, 0xbfb8aa3b, v173
	v_exp_f32_e32 v2, v2
	v_exp_f32_e32 v3, v3
	v_exp_f32_e32 v170, v170
	v_exp_f32_e32 v171, v171
	v_add_f32_e32 v172, 1.0, v182
	v_add_f32_e32 v182, 1.0, v184
	v_exp_f32_e32 v183, v183
	v_exp_f32_e32 v184, v173
	v_add_f32_e32 v2, 1.0, v2
	v_add_f32_e32 v3, 1.0, v3
	v_add_f32_e32 v170, 1.0, v170
	v_add_f32_e32 v171, 1.0, v171
	v_rcp_f32_e32 v173, v182
	v_add_f32_e32 v182, 1.0, v183
	v_add_f32_e32 v183, 1.0, v184
	v_rcp_f32_e32 v2, v2
	v_rcp_f32_e32 v3, v3
	v_rcp_f32_e32 v170, v170
	v_rcp_f32_e32 v171, v171
	v_rcp_f32_e32 v172, v172
	v_rcp_f32_e32 v182, v182
	v_rcp_f32_e32 v183, v183
	v_pk_mul_f32 v[2:3], v[64:65], v[2:3]
	v_pk_mul_f32 v[184:185], v[66:67], v[170:171]
	v_pk_mul_f32 v[172:173], v[60:61], v[172:173]
	v_pk_mul_f32 v[182:183], v[62:63], v[182:183]
	v_cvt_pk_bf16_f32 v170, v2, v3
	v_cvt_pk_bf16_f32 v171, v184, v185
	v_cvt_pk_bf16_f32 v172, v172, v173
	v_cvt_pk_bf16_f32 v173, v182, v183
	global_store_dwordx4 v169, v[170:173], s[4:5]
	v_lshlrev_b32_e32 v169, 16, v175
	v_mul_f32_e32 v169, 0xbfb8aa3b, v169
	v_and_b32_e32 v170, 0xffff0000, v175
	v_exp_f32_e32 v169, v169
	v_mul_f32_e32 v170, 0xbfb8aa3b, v170
	v_exp_f32_e32 v175, v170
	v_lshlrev_b32_e32 v171, 16, v176
	v_and_b32_e32 v172, 0xffff0000, v176
	v_add_f32_e32 v169, 1.0, v169
	v_mul_f32_e32 v171, 0xbfb8aa3b, v171
	v_rcp_f32_e32 v170, v169
	v_add_f32_e32 v169, 1.0, v175
	v_exp_f32_e32 v175, v171
	v_mul_f32_e32 v171, 0xbfb8aa3b, v172
	v_exp_f32_e32 v176, v171
	v_lshlrev_b32_e32 v173, 16, v177
	v_lshlrev_b32_e32 v2, 16, v174
	v_and_b32_e32 v3, 0xffff0000, v174
	v_and_b32_e32 v174, 0xffff0000, v177
	v_mul_f32_e32 v173, 0xbfb8aa3b, v173
	v_mul_f32_e32 v2, 0xbfb8aa3b, v2
	v_mul_f32_e32 v3, 0xbfb8aa3b, v3
; __device__ __forceinline__ float sigmoidf_(float x) { return __builtin_amdgcn_rcpf(1.0f + __expf(-x)); }
;     __device__ __forceinline__ void operator()(f32x4 (&acc)[2][2][4][2], const pg8::Unit& u, int wr, int wc, int fr, int fq) const {
;     ...
;         for (int ai = 0; ai < 2; ++ai) {
;             u32x4 ga[4][2];
; #pragma unroll
;             for (int m = 0; m < 4; ++m)
; #pragma unroll
;                 for (int bj = 0; bj < 2; ++bj) ga[m][bj] = __builtin_nontemporal_load((const u32x4*)((const char*)Gt + (goff + (unsigned)(ai * 128 + m * 16) * 4096u + 256u * bj)));
; #pragma unroll
;             for (int m = 0; m < 4; ++m) {
;                 const unsigned rm = moff + (unsigned)(ai * 128 + m * 16) * 2048u;
; #pragma unroll
;                 for (int bj = 0; bj < 2; ++bj) {
;                     float fa[8], o[8]; unpack8(ga[m][bj], fa);
; #pragma unroll
;                     for (int e = 0; e < 8; ++e) o[e] = sigmoidf_(fa[e]) * acc[ai][bj][m][e >> 2][e & 3];
;                     *(u32x4*)((char*)MG + (rm + 256u * bj)) = pack8(o);
;                 }
;             }
;             asm volatile("" ::: "memory");
;         }
	v_rcp_f32_e32 v171, v169
	v_add_f32_e32 v169, 1.0, v175
	v_exp_f32_e32 v175, v173
	v_mul_f32_e32 v173, 0xbfb8aa3b, v174
	v_exp_f32_e32 v2, v2
	v_exp_f32_e32 v3, v3
	v_rcp_f32_e32 v172, v169
	v_add_f32_e32 v169, 1.0, v176
	v_exp_f32_e32 v176, v173
	v_rcp_f32_e32 v173, v169
	v_add_f32_e32 v169, 1.0, v175
	v_add_f32_e32 v2, 1.0, v2
	v_add_f32_e32 v3, 1.0, v3
	v_rcp_f32_e32 v174, v169
	v_add_f32_e32 v169, 1.0, v176
	v_rcp_f32_e32 v2, v2
	v_rcp_f32_e32 v3, v3
	v_rcp_f32_e32 v175, v169
	v_pk_mul_f32 v[176:177], v[34:35], v[170:171]
	v_pk_mul_f32 v[172:173], v[28:29], v[172:173]
	v_pk_mul_f32 v[2:3], v[32:33], v[2:3]
	v_pk_mul_f32 v[174:175], v[30:31], v[174:175]
	v_cvt_pk_bf16_f32 v170, v2, v3
	v_cvt_pk_bf16_f32 v171, v176, v177
	v_cvt_pk_bf16_f32 v172, v172, v173
	v_cvt_pk_bf16_f32 v173, v174, v175
	v_add_u32_e32 v2, 0x40100, v0
	global_store_dwordx4 v2, v[170:173], s[4:5]
	v_lshlrev_b32_e32 v2, 16, v178
	v_and_b32_e32 v3, 0xffff0000, v178
	v_lshlrev_b32_e32 v170, 16, v179
	v_and_b32_e32 v171, 0xffff0000, v179
	v_lshlrev_b32_e32 v172, 16, v180
	v_and_b32_e32 v173, 0xffff0000, v180
	v_lshlrev_b32_e32 v174, 16, v181
	v_and_b32_e32 v175, 0xffff0000, v181
	v_mul_f32_e32 v2, 0xbfb8aa3b, v2
	v_mul_f32_e32 v3, 0xbfb8aa3b, v3
	v_mul_f32_e32 v170, 0xbfb8aa3b, v170
	v_mul_f32_e32 v171, 0xbfb8aa3b, v171
	v_mul_f32_e32 v172, 0xbfb8aa3b, v172
	v_mul_f32_e32 v173, 0xbfb8aa3b, v173
	v_mul_f32_e32 v174, 0xbfb8aa3b, v174
	v_mul_f32_e32 v175, 0xbfb8aa3b, v175
	v_exp_f32_e32 v2, v2
	v_exp_f32_e32 v3, v3
	v_exp_f32_e32 v170, v170
	v_exp_f32_e32 v171, v171
	v_exp_f32_e32 v172, v172
	v_exp_f32_e32 v173, v173
	v_exp_f32_e32 v174, v174
	v_exp_f32_e32 v175, v175
	v_add_f32_e32 v2, 1.0, v2
	v_add_f32_e32 v3, 1.0, v3
	v_add_f32_e32 v170, 1.0, v170
	v_add_f32_e32 v171, 1.0, v171
	v_add_f32_e32 v172, 1.0, v172
	v_add_f32_e32 v173, 1.0, v173
	v_add_f32_e32 v174, 1.0, v174
	v_add_f32_e32 v175, 1.0, v175
	v_rcp_f32_e32 v2, v2
	v_rcp_f32_e32 v3, v3
	v_rcp_f32_e32 v170, v170
	v_rcp_f32_e32 v171, v171
	v_rcp_f32_e32 v172, v172
	v_rcp_f32_e32 v173, v173
	v_rcp_f32_e32 v174, v174
	v_rcp_f32_e32 v175, v175
	v_pk_mul_f32 v[2:3], v[56:57], v[2:3]
	v_pk_mul_f32 v[176:177], v[58:59], v[170:171]
	v_pk_mul_f32 v[172:173], v[52:53], v[172:173]
	v_pk_mul_f32 v[174:175], v[54:55], v[174:175]
	v_add_u32_e32 v169, 0x48000, v0
	v_cvt_pk_bf16_f32 v170, v2, v3
	v_cvt_pk_bf16_f32 v171, v176, v177
	v_cvt_pk_bf16_f32 v172, v172, v173
	v_cvt_pk_bf16_f32 v173, v174, v175
	global_store_dwordx4 v169, v[170:173], s[4:5]
	v_lshlrev_b32_e32 v169, 16, v150
	v_and_b32_e32 v150, 0xffff0000, v150
	v_mul_f32_e32 v169, 0xbfb8aa3b, v169
	v_mul_f32_e32 v150, 0xbfb8aa3b, v150
	v_exp_f32_e32 v169, v169
	v_exp_f32_e32 v171, v150
	v_lshlrev_b32_e32 v170, 16, v151
	v_lshlrev_b32_e32 v2, 16, v148
	v_and_b32_e32 v3, 0xffff0000, v148
	v_lshlrev_b32_e32 v148, 16, v149
	v_and_b32_e32 v149, 0xffff0000, v149
	v_and_b32_e32 v151, 0xffff0000, v151
	v_mul_f32_e32 v170, 0xbfb8aa3b, v170
	v_mul_f32_e32 v2, 0xbfb8aa3b, v2
	v_mul_f32_e32 v3, 0xbfb8aa3b, v3
	v_mul_f32_e32 v148, 0xbfb8aa3b, v148
	v_mul_f32_e32 v149, 0xbfb8aa3b, v149
	v_exp_f32_e32 v170, v170
	v_mul_f32_e32 v151, 0xbfb8aa3b, v151
	v_exp_f32_e32 v2, v2
	v_exp_f32_e32 v3, v3
	v_exp_f32_e32 v148, v148
	v_exp_f32_e32 v149, v149
	v_add_f32_e32 v150, 1.0, v169
	v_add_f32_e32 v169, 1.0, v171
	v_exp_f32_e32 v171, v151
	v_rcp_f32_e32 v151, v169
	v_add_f32_e32 v169, 1.0, v170
	v_add_f32_e32 v2, 1.0, v2
	v_add_f32_e32 v3, 1.0, v3
	v_add_f32_e32 v148, 1.0, v148
	v_add_f32_e32 v149, 1.0, v149
	v_rcp_f32_e32 v170, v169
	v_add_f32_e32 v169, 1.0, v171
	v_rcp_f32_e32 v2, v2
	v_rcp_f32_e32 v3, v3
	v_rcp_f32_e32 v148, v148
	v_rcp_f32_e32 v149, v149
	v_rcp_f32_e32 v150, v150
	v_rcp_f32_e32 v171, v169
	v_pk_mul_f32 v[2:3], v[24:25], v[2:3]
	v_pk_mul_f32 v[172:173], v[26:27], v[148:149]
	v_pk_mul_f32 v[150:151], v[20:21], v[150:151]
	v_pk_mul_f32 v[170:171], v[22:23], v[170:171]
	v_cvt_pk_bf16_f32 v148, v2, v3
	v_cvt_pk_bf16_f32 v149, v172, v173
	v_cvt_pk_bf16_f32 v150, v150, v151
	v_cvt_pk_bf16_f32 v151, v170, v171
	v_add_u32_e32 v2, 0x48100, v0
	global_store_dwordx4 v2, v[148:151], s[4:5]
	v_lshlrev_b32_e32 v2, 16, v144
	v_and_b32_e32 v3, 0xffff0000, v144
	v_lshlrev_b32_e32 v148, 16, v146
	v_and_b32_e32 v146, 0xffff0000, v146
	v_mul_f32_e32 v148, 0xbfb8aa3b, v148
	v_mul_f32_e32 v146, 0xbfb8aa3b, v146
	v_exp_f32_e32 v148, v148
	v_exp_f32_e32 v150, v146
	v_lshlrev_b32_e32 v144, 16, v145
	v_and_b32_e32 v145, 0xffff0000, v145
	v_lshlrev_b32_e32 v149, 16, v147
	v_and_b32_e32 v147, 0xffff0000, v147
	v_mul_f32_e32 v2, 0xbfb8aa3b, v2
	v_mul_f32_e32 v3, 0xbfb8aa3b, v3
	v_mul_f32_e32 v144, 0xbfb8aa3b, v144
	v_mul_f32_e32 v145, 0xbfb8aa3b, v145
	v_mul_f32_e32 v149, 0xbfb8aa3b, v149
	v_mul_f32_e32 v147, 0xbfb8aa3b, v147
	v_exp_f32_e32 v2, v2
	v_exp_f32_e32 v3, v3
	v_exp_f32_e32 v144, v144
	v_exp_f32_e32 v145, v145
	v_add_f32_e32 v146, 1.0, v148
	v_add_f32_e32 v148, 1.0, v150
	v_exp_f32_e32 v149, v149
	v_exp_f32_e32 v150, v147
	v_add_f32_e32 v2, 1.0, v2
	v_add_f32_e32 v3, 1.0, v3
	v_add_f32_e32 v144, 1.0, v144
	v_add_f32_e32 v145, 1.0, v145
	v_rcp_f32_e32 v147, v148
	v_add_f32_e32 v148, 1.0, v149
	v_add_f32_e32 v149, 1.0, v150
	v_rcp_f32_e32 v2, v2
	v_rcp_f32_e32 v3, v3
	v_rcp_f32_e32 v144, v144
	v_rcp_f32_e32 v145, v145
	v_rcp_f32_e32 v146, v146
; __device__ __forceinline__ float sigmoidf_(float x) { return __builtin_amdgcn_rcpf(1.0f + __expf(-x)); }
;     __device__ __forceinline__ void operator()(f32x4 (&acc)[2][2][4][2], const pg8::Unit& u, int wr, int wc, int fr, int fq) const {
;     ...
;         for (int ai = 0; ai < 2; ++ai) {
;             u32x4 ga[4][2];
; #pragma unroll
;             for (int m = 0; m < 4; ++m)
; #pragma unroll
;                 for (int bj = 0; bj < 2; ++bj) ga[m][bj] = __builtin_nontemporal_load((const u32x4*)((const char*)Gt + (goff + (unsigned)(ai * 128 + m * 16) * 4096u + 256u * bj)));
; #pragma unroll
;             for (int m = 0; m < 4; ++m) {
;                 const unsigned rm = moff + (unsigned)(ai * 128 + m * 16) * 2048u;
; #pragma unroll
;                 for (int bj = 0; bj < 2; ++bj) {
;                     float fa[8], o[8]; unpack8(ga[m][bj], fa);
; #pragma unroll
;                     for (int e = 0; e < 8; ++e) o[e] = sigmoidf_(fa[e]) * acc[ai][bj][m][e >> 2][e & 3];
;                     *(u32x4*)((char*)MG + (rm + 256u * bj)) = pack8(o);
;                 }
;             }
;             asm volatile("" ::: "memory");
;         }
	v_rcp_f32_e32 v148, v148
	v_rcp_f32_e32 v149, v149
	v_pk_mul_f32 v[2:3], v[48:49], v[2:3]
	v_pk_mul_f32 v[150:151], v[50:51], v[144:145]
	v_pk_mul_f32 v[146:147], v[44:45], v[146:147]
	v_pk_mul_f32 v[148:149], v[46:47], v[148:149]
	v_add_u32_e32 v169, 0x50000, v0
	v_cvt_pk_bf16_f32 v144, v2, v3
	v_cvt_pk_bf16_f32 v145, v150, v151
	v_cvt_pk_bf16_f32 v146, v146, v147
	v_cvt_pk_bf16_f32 v147, v148, v149
	global_store_dwordx4 v169, v[144:147], s[4:5]
	v_lshlrev_b32_e32 v2, 16, v140
	v_and_b32_e32 v3, 0xffff0000, v140
	v_lshlrev_b32_e32 v144, 16, v142
	v_and_b32_e32 v142, 0xffff0000, v142
	v_mul_f32_e32 v144, 0xbfb8aa3b, v144
	v_mul_f32_e32 v142, 0xbfb8aa3b, v142
	v_exp_f32_e32 v144, v144
	v_exp_f32_e32 v146, v142
	v_lshlrev_b32_e32 v140, 16, v141
	v_and_b32_e32 v141, 0xffff0000, v141
	v_lshlrev_b32_e32 v145, 16, v143
	v_and_b32_e32 v143, 0xffff0000, v143
	v_mul_f32_e32 v2, 0xbfb8aa3b, v2
	v_mul_f32_e32 v3, 0xbfb8aa3b, v3
	v_mul_f32_e32 v140, 0xbfb8aa3b, v140
	v_mul_f32_e32 v141, 0xbfb8aa3b, v141
	v_mul_f32_e32 v145, 0xbfb8aa3b, v145
	v_mul_f32_e32 v143, 0xbfb8aa3b, v143
	v_exp_f32_e32 v2, v2
	v_exp_f32_e32 v3, v3
	v_exp_f32_e32 v140, v140
	v_exp_f32_e32 v141, v141
	v_add_f32_e32 v142, 1.0, v144
	v_add_f32_e32 v144, 1.0, v146
	v_exp_f32_e32 v145, v145
	v_exp_f32_e32 v146, v143
	v_add_f32_e32 v2, 1.0, v2
	v_add_f32_e32 v3, 1.0, v3
	v_add_f32_e32 v140, 1.0, v140
	v_add_f32_e32 v141, 1.0, v141
	v_rcp_f32_e32 v143, v144
	v_add_f32_e32 v144, 1.0, v145
	v_add_f32_e32 v145, 1.0, v146
	v_rcp_f32_e32 v2, v2
	v_rcp_f32_e32 v3, v3
	v_rcp_f32_e32 v140, v140
	v_rcp_f32_e32 v141, v141
	v_rcp_f32_e32 v142, v142
	v_rcp_f32_e32 v144, v144
	v_rcp_f32_e32 v145, v145
	v_pk_mul_f32 v[2:3], v[16:17], v[2:3]
	v_pk_mul_f32 v[146:147], v[18:19], v[140:141]
	v_pk_mul_f32 v[142:143], v[12:13], v[142:143]
	v_pk_mul_f32 v[144:145], v[14:15], v[144:145]
	v_cvt_pk_bf16_f32 v140, v2, v3
	v_cvt_pk_bf16_f32 v141, v146, v147
	v_cvt_pk_bf16_f32 v142, v142, v143
	v_cvt_pk_bf16_f32 v143, v144, v145
	v_add_u32_e32 v2, 0x50100, v0
	global_store_dwordx4 v2, v[140:143], s[4:5]
	v_lshlrev_b32_e32 v2, 16, v136
	v_and_b32_e32 v3, 0xffff0000, v136
	v_lshlrev_b32_e32 v140, 16, v138
	v_and_b32_e32 v138, 0xffff0000, v138
	v_mul_f32_e32 v140, 0xbfb8aa3b, v140
	v_mul_f32_e32 v138, 0xbfb8aa3b, v138
	v_exp_f32_e32 v140, v140
	v_exp_f32_e32 v142, v138
	v_lshlrev_b32_e32 v136, 16, v137
	v_and_b32_e32 v137, 0xffff0000, v137
	v_lshlrev_b32_e32 v141, 16, v139
	v_and_b32_e32 v139, 0xffff0000, v139
	v_mul_f32_e32 v2, 0xbfb8aa3b, v2
	v_mul_f32_e32 v3, 0xbfb8aa3b, v3
	v_mul_f32_e32 v136, 0xbfb8aa3b, v136
	v_mul_f32_e32 v137, 0xbfb8aa3b, v137
	v_mul_f32_e32 v141, 0xbfb8aa3b, v141
	v_mul_f32_e32 v139, 0xbfb8aa3b, v139
	v_exp_f32_e32 v2, v2
	v_exp_f32_e32 v3, v3
	v_exp_f32_e32 v136, v136
	v_exp_f32_e32 v137, v137
	v_add_f32_e32 v138, 1.0, v140
	v_add_f32_e32 v140, 1.0, v142
	v_exp_f32_e32 v141, v141
	v_exp_f32_e32 v142, v139
	v_add_f32_e32 v2, 1.0, v2
	v_add_f32_e32 v3, 1.0, v3
	v_add_f32_e32 v136, 1.0, v136
	v_add_f32_e32 v137, 1.0, v137
	v_rcp_f32_e32 v139, v140
	v_add_f32_e32 v140, 1.0, v141
	v_add_f32_e32 v141, 1.0, v142
	v_rcp_f32_e32 v2, v2
	v_rcp_f32_e32 v3, v3
	v_rcp_f32_e32 v136, v136
	v_rcp_f32_e32 v137, v137
	v_rcp_f32_e32 v138, v138
	v_rcp_f32_e32 v140, v140
	v_rcp_f32_e32 v141, v141
	v_pk_mul_f32 v[2:3], v[40:41], v[2:3]
	v_pk_mul_f32 v[142:143], v[42:43], v[136:137]
	v_pk_mul_f32 v[138:139], v[36:37], v[138:139]
	v_pk_mul_f32 v[140:141], v[38:39], v[140:141]
	v_add_u32_e32 v144, 0x58000, v0
	v_cvt_pk_bf16_f32 v136, v2, v3
	v_cvt_pk_bf16_f32 v137, v142, v143
	v_cvt_pk_bf16_f32 v138, v138, v139
	v_cvt_pk_bf16_f32 v139, v140, v141
	global_store_dwordx4 v144, v[136:139], s[4:5]
	v_lshlrev_b32_e32 v2, 16, v132
	v_and_b32_e32 v3, 0xffff0000, v132
	v_lshlrev_b32_e32 v136, 16, v134
	v_and_b32_e32 v134, 0xffff0000, v134
	v_mul_f32_e32 v136, 0xbfb8aa3b, v136
	v_mul_f32_e32 v134, 0xbfb8aa3b, v134
	v_exp_f32_e32 v136, v136
	v_exp_f32_e32 v138, v134
	v_lshlrev_b32_e32 v132, 16, v133
	v_and_b32_e32 v133, 0xffff0000, v133
	v_lshlrev_b32_e32 v137, 16, v135
	v_and_b32_e32 v135, 0xffff0000, v135
	v_mul_f32_e32 v2, 0xbfb8aa3b, v2
	v_mul_f32_e32 v3, 0xbfb8aa3b, v3
	v_mul_f32_e32 v132, 0xbfb8aa3b, v132
	v_mul_f32_e32 v133, 0xbfb8aa3b, v133
	v_mul_f32_e32 v137, 0xbfb8aa3b, v137
	v_mul_f32_e32 v135, 0xbfb8aa3b, v135
	v_exp_f32_e32 v2, v2
	v_exp_f32_e32 v3, v3
	v_exp_f32_e32 v132, v132
	v_exp_f32_e32 v133, v133
	v_add_f32_e32 v134, 1.0, v136
	v_add_f32_e32 v136, 1.0, v138
	v_exp_f32_e32 v137, v137
	v_exp_f32_e32 v138, v135
	v_add_f32_e32 v2, 1.0, v2
	v_add_f32_e32 v3, 1.0, v3
	v_add_f32_e32 v132, 1.0, v132
	v_add_f32_e32 v133, 1.0, v133
	v_rcp_f32_e32 v135, v136
	v_add_f32_e32 v136, 1.0, v137
	v_add_f32_e32 v137, 1.0, v138
	v_rcp_f32_e32 v2, v2
	v_rcp_f32_e32 v3, v3
	v_rcp_f32_e32 v132, v132
	v_rcp_f32_e32 v133, v133
	v_rcp_f32_e32 v134, v134
	v_rcp_f32_e32 v136, v136
	v_rcp_f32_e32 v137, v137
	v_pk_mul_f32 v[2:3], v[8:9], v[2:3]
	v_pk_mul_f32 v[138:139], v[10:11], v[132:133]
	v_pk_mul_f32 v[134:135], v[4:5], v[134:135]
	v_pk_mul_f32 v[136:137], v[6:7], v[136:137]
	v_cvt_pk_bf16_f32 v132, v2, v3
	v_cvt_pk_bf16_f32 v133, v138, v139
	v_cvt_pk_bf16_f32 v134, v134, v135
	v_cvt_pk_bf16_f32 v135, v136, v137
	v_add_u32_e32 v0, 0x58100, v0
	global_store_dwordx4 v0, v[132:135], s[4:5]
